# GLU and in-proj epilogues: xor-16/xor-32 row-sum shuffles via v_permlane16/32_swap instead of ds_bpermute (on top of v23)
# baseline (speedup 1.0000x reference)
; __device__ __forceinline__ u32x4 pack8(f32x4 v0, f32x4 v1) { u32x4 w; w.x = cvt_pk_bf16(v0[0], v0[1]); w.y = cvt_pk_bf16(v0[2], v0[3]); w.z = cvt_pk_bf16(v1[0], v1[1]); w.w = cvt_pk_bf16(v1[2], v1[3]); return w; }
;     __device__ __forceinline__ void operator()(EPI_ARGS) const {
;     ...
;         if (pn <= 2) {
;             bf16_t* base = pn < 2 ? CQ : CKV; const int ld = pn < 2 ? 512 : 256, colt = pn < 2 ? pn * 256 : 0; float* rs = pn < 2 ? rsq_q : rsq_kv;
; #pragma unroll
;             for (int ai = 0; ai < 2; ++ai)
; #pragma unroll
;                 for (int m = 0; m < 4; ++m) { const int row = EPI_ROW(ai, m); float ss = 0.f;
; #pragma unroll
;                     for (int bj = 0; bj < 2; ++bj) { const f32x4 v0 = acc[ai][bj][m][0], v1 = acc[ai][bj][m][1];
;                         ss += (v0[0] * v0[0] + v0[1] * v0[1]) + (v0[2] * v0[2] + v0[3] * v0[3]) + (v1[0] * v1[0] + v1[1] * v1[1]) + (v1[2] * v1[2] + v1[3] * v1[3]);
;                         *(u32x4*)(base + (size_t)row * ld + colt + bj * 128 + wc * 32 + 8 * fq) = pack8(v0, v1); }
;                     ss += __shfl_xor(ss, 16); ss += __shfl_xor(ss, 32);
;                     if (fq == 0) atomicAdd(rs + row, ss); }
.LBB0_202:
	v_mul_f32_e32 v167, v125, v125
	v_mul_f32_e32 v170, v127, v127
	v_fmac_f32_e32 v167, v124, v124
	v_fmac_f32_e32 v170, v126, v126
	v_add_f32_e32 v167, v167, v170
	v_mul_f32_e32 v170, v121, v121
	v_fmac_f32_e32 v170, v120, v120
	v_cvt_pk_bf16_f32 v124, v124, v125
	v_cvt_pk_bf16_f32 v125, v126, v127
	v_cvt_pk_bf16_f32 v126, v120, v121
	v_mul_f32_e32 v120, v117, v117
	v_mul_f32_e32 v121, v119, v119
	v_fmac_f32_e32 v120, v116, v116
	v_fmac_f32_e32 v121, v118, v118
	s_lshl_b32 s10, s90, 8
	v_add_f32_e32 v120, v120, v121
	v_mul_f32_e32 v121, v113, v113
	s_cmp_eq_u32 s90, 2
	v_fmac_f32_e32 v121, v112, v112
	s_cselect_b32 s38, 0, s10
	v_add_f32_e32 v167, v167, v170
	v_mul_f32_e32 v170, v123, v123
	v_add_f32_e32 v120, v120, v121
	v_mul_f32_e32 v121, v115, v115
	s_cselect_b32 s15, s61, s59
	s_cselect_b32 s46, s60, s24
	s_cselect_b32 s11, s31, s77
	s_cselect_b32 s10, s30, s76
	s_cselect_b32 s14, 8, 9
	s_ashr_i32 s39, s38, 31
	v_fmac_f32_e32 v170, v122, v122
	v_fmac_f32_e32 v121, v114, v114
	s_lshl_b64 s[38:39], s[38:39], 1
	v_add_f32_e32 v167, v170, v167
	v_add_f32_e32 v120, v121, v120
	v_and_b32_e32 v127, 64, v166
	s_add_u32 s38, s46, s38
	v_add_f32_e32 v121, v167, v120
	v_xor_b32_e32 v120, 16, v166
	v_add_u32_e32 v167, 64, v127
	s_addc_u32 s15, s15, s39
	v_cmp_lt_i32_e32 vcc, v120, v167
	v_lshl_add_u32 v148, s89, 8, v156
	s_add_u32 s38, s38, s81
	v_cndmask_b32_e32 v120, v166, v120, vcc
	s_addc_u32 s39, s15, 0
	v_ashrrev_i32_e32 v149, 31, v148
	v_lshlrev_b32_e32 v120, 2, v120
	v_lshl_add_u64 v[150:151], s[38:39], 0, v[134:135]
	v_lshlrev_b64 v[152:153], s14, v[148:149]
	v_mov_b32_e32 v244, v121
	v_mov_b32_e32 v170, v121
	s_nop 1
	v_permlane16_swap_b32_e32 v244, v170
	v_lshl_add_u64 v[152:153], v[152:153], 1, v[150:151]
	v_cvt_pk_bf16_f32 v127, v122, v123
	global_store_dwordx4 v[152:153], v[124:127], off
	v_cvt_pk_bf16_f32 v122, v116, v117
	v_xor_b32_e32 v116, 32, v166
	v_cmp_lt_i32_e32 vcc, v116, v167
	s_waitcnt lgkmcnt(0)
	v_add_f32_e32 v117, v121, v170
	v_cvt_pk_bf16_f32 v123, v118, v119
	v_cvt_pk_bf16_f32 v124, v112, v113
	v_lshl_add_u64 v[112:113], v[148:149], 2, s[10:11]
	v_cndmask_b32_e32 v116, v166, v116, vcc
	v_lshlrev_b32_e32 v116, 2, v116
	v_mov_b32_e32 v244, v117
	v_mov_b32_e32 v118, v117
	s_nop 1
	v_permlane32_swap_b32_e32 v244, v118
	v_cvt_pk_bf16_f32 v125, v114, v115
	global_store_dwordx4 v[152:153], v[122:125], off offset:256
	s_and_saveexec_b64 s[10:11], s[4:5]
	s_cbranch_execz .LBB0_204
	s_waitcnt lgkmcnt(0)
	v_add_f32_e32 v114, v117, v118
	global_atomic_add_f32 v[112:113], v114, off
.LBB0_204:
	s_or_b64 exec, exec, s[10:11]
	v_mul_f32_e32 v117, v109, v109
	s_waitcnt lgkmcnt(0)
	v_mul_f32_e32 v118, v111, v111
	v_fmac_f32_e32 v117, v108, v108
	v_fmac_f32_e32 v118, v110, v110
	v_cvt_pk_bf16_f32 v108, v108, v109
	v_cvt_pk_bf16_f32 v109, v110, v111
	v_mul_f32_e32 v110, v101, v101
	v_mul_f32_e32 v111, v103, v103
	v_fmac_f32_e32 v110, v100, v100
	v_fmac_f32_e32 v111, v102, v102
	v_add_f32_e32 v117, v117, v118
	v_mul_f32_e32 v118, v105, v105
	v_add_f32_e32 v110, v110, v111
	v_mul_f32_e32 v111, v97, v97
	v_fmac_f32_e32 v118, v104, v104
	v_fmac_f32_e32 v111, v96, v96
	v_add_f32_e32 v117, v117, v118
	v_mul_f32_e32 v118, v107, v107
	v_add_f32_e32 v110, v110, v111
	v_mul_f32_e32 v111, v99, v99
	v_fmac_f32_e32 v118, v106, v106
	v_fmac_f32_e32 v111, v98, v98
	v_add_f32_e32 v117, v118, v117
	v_add_f32_e32 v110, v111, v110
	v_add_f32_e32 v117, v117, v110
	v_mov_b32_e32 v244, v117
	v_mov_b32_e32 v118, v117
	s_nop 1
	v_permlane16_swap_b32_e32 v244, v118
	v_or_b32_e32 v114, 16, v148
	v_ashrrev_i32_e32 v115, 31, v114
	v_lshlrev_b64 v[114:115], s14, v[114:115]
	v_lshl_add_u64 v[114:115], v[114:115], 1, v[150:151]
	v_cvt_pk_bf16_f32 v110, v104, v105
	v_cvt_pk_bf16_f32 v111, v106, v107
	global_store_dwordx4 v[114:115], v[108:111], off
	v_cvt_pk_bf16_f32 v104, v100, v101
	s_waitcnt lgkmcnt(0)
	v_add_f32_e32 v100, v117, v118
	v_mov_b32_e32 v244, v100
	v_mov_b32_e32 v101, v100
	s_nop 1
	v_permlane32_swap_b32_e32 v244, v101
	v_cvt_pk_bf16_f32 v105, v102, v103
	v_cvt_pk_bf16_f32 v106, v96, v97
	v_cvt_pk_bf16_f32 v107, v98, v99
	global_store_dwordx4 v[114:115], v[104:107], off offset:256
	s_and_saveexec_b64 s[10:11], s[4:5]
	s_cbranch_execz .LBB0_206
	s_waitcnt lgkmcnt(0)
	v_add_f32_e32 v96, v100, v101
	global_atomic_add_f32 v[112:113], v96, off offset:64
.LBB0_206:
	s_or_b64 exec, exec, s[10:11]
	v_mul_f32_e32 v98, v93, v93
	v_mul_f32_e32 v99, v95, v95
	v_fmac_f32_e32 v98, v92, v92
	v_fmac_f32_e32 v99, v94, v94
	v_cvt_pk_bf16_f32 v92, v92, v93
	v_cvt_pk_bf16_f32 v93, v94, v95
	v_mul_f32_e32 v94, v85, v85
	v_mul_f32_e32 v95, v87, v87
	v_fmac_f32_e32 v94, v84, v84
	v_fmac_f32_e32 v95, v86, v86
	v_add_f32_e32 v98, v98, v99
	v_mul_f32_e32 v99, v89, v89
	v_add_f32_e32 v94, v94, v95
	v_mul_f32_e32 v95, v81, v81
	v_fmac_f32_e32 v99, v88, v88
	v_fmac_f32_e32 v95, v80, v80
	v_add_f32_e32 v98, v98, v99
	v_mul_f32_e32 v99, v91, v91
	v_add_f32_e32 v94, v94, v95
	v_mul_f32_e32 v95, v83, v83
	v_fmac_f32_e32 v99, v90, v90
	v_fmac_f32_e32 v95, v82, v82
	v_add_f32_e32 v98, v99, v98
	v_add_f32_e32 v94, v95, v94
	v_add_f32_e32 v98, v98, v94
	v_mov_b32_e32 v244, v98
	v_mov_b32_e32 v99, v98
	s_nop 1
	v_permlane16_swap_b32_e32 v244, v99
	v_or_b32_e32 v96, 32, v148
	v_ashrrev_i32_e32 v97, 31, v96
	v_lshlrev_b64 v[96:97], s14, v[96:97]
	v_lshl_add_u64 v[96:97], v[96:97], 1, v[150:151]
	v_cvt_pk_bf16_f32 v94, v88, v89
	v_cvt_pk_bf16_f32 v95, v90, v91
	global_store_dwordx4 v[96:97], v[92:95], off
	v_cvt_pk_bf16_f32 v88, v84, v85
	s_waitcnt lgkmcnt(0)
	v_add_f32_e32 v84, v98, v99
	v_mov_b32_e32 v244, v84
	v_mov_b32_e32 v85, v84
	s_nop 1
	v_permlane32_swap_b32_e32 v244, v85
	v_cvt_pk_bf16_f32 v89, v86, v87
	v_cvt_pk_bf16_f32 v90, v80, v81
	v_cvt_pk_bf16_f32 v91, v82, v83
	global_store_dwordx4 v[96:97], v[88:91], off offset:256
	s_and_saveexec_b64 s[10:11], s[4:5]
	s_cbranch_execz .LBB0_208
	s_waitcnt lgkmcnt(0)
	v_add_f32_e32 v80, v84, v85
	global_atomic_add_f32 v[112:113], v80, off offset:128
; __device__ __forceinline__ u32x4 pack8(f32x4 v0, f32x4 v1) { u32x4 w; w.x = cvt_pk_bf16(v0[0], v0[1]); w.y = cvt_pk_bf16(v0[2], v0[3]); w.z = cvt_pk_bf16(v1[0], v1[1]); w.w = cvt_pk_bf16(v1[2], v1[3]); return w; }
;     __device__ __forceinline__ void operator()(EPI_ARGS) const {
;     ...
;         if (pn <= 2) {
;             bf16_t* base = pn < 2 ? CQ : CKV; const int ld = pn < 2 ? 512 : 256, colt = pn < 2 ? pn * 256 : 0; float* rs = pn < 2 ? rsq_q : rsq_kv;
; #pragma unroll
;             for (int ai = 0; ai < 2; ++ai)
; #pragma unroll
;                 for (int m = 0; m < 4; ++m) { const int row = EPI_ROW(ai, m); float ss = 0.f;
; #pragma unroll
;                     for (int bj = 0; bj < 2; ++bj) { const f32x4 v0 = acc[ai][bj][m][0], v1 = acc[ai][bj][m][1];
;                         ss += (v0[0] * v0[0] + v0[1] * v0[1]) + (v0[2] * v0[2] + v0[3] * v0[3]) + (v1[0] * v1[0] + v1[1] * v1[1]) + (v1[2] * v1[2] + v1[3] * v1[3]);
;                         *(u32x4*)(base + (size_t)row * ld + colt + bj * 128 + wc * 32 + 8 * fq) = pack8(v0, v1); }
;                     ss += __shfl_xor(ss, 16); ss += __shfl_xor(ss, 32);
;                     if (fq == 0) atomicAdd(rs + row, ss); }
.LBB0_208:
	s_or_b64 exec, exec, s[10:11]
	v_mul_f32_e32 v82, v77, v77
	v_mul_f32_e32 v83, v79, v79
	v_fmac_f32_e32 v82, v76, v76
	v_fmac_f32_e32 v83, v78, v78
	v_cvt_pk_bf16_f32 v76, v76, v77
	v_cvt_pk_bf16_f32 v77, v78, v79
	v_mul_f32_e32 v78, v69, v69
	v_mul_f32_e32 v79, v71, v71
	v_fmac_f32_e32 v78, v68, v68
	v_fmac_f32_e32 v79, v70, v70
	v_add_f32_e32 v82, v82, v83
	v_mul_f32_e32 v83, v73, v73
	v_add_f32_e32 v78, v78, v79
	v_mul_f32_e32 v79, v65, v65
	v_fmac_f32_e32 v83, v72, v72
	v_fmac_f32_e32 v79, v64, v64
	v_add_f32_e32 v82, v82, v83
	v_mul_f32_e32 v83, v75, v75
	v_add_f32_e32 v78, v78, v79
	v_mul_f32_e32 v79, v67, v67
	v_fmac_f32_e32 v83, v74, v74
	v_fmac_f32_e32 v79, v66, v66
	v_add_f32_e32 v82, v83, v82
	v_add_f32_e32 v78, v79, v78
	v_add_f32_e32 v82, v82, v78
	v_mov_b32_e32 v244, v82
	v_mov_b32_e32 v83, v82
	s_nop 1
	v_permlane16_swap_b32_e32 v244, v83
	v_or_b32_e32 v80, 48, v148
	v_ashrrev_i32_e32 v81, 31, v80
	v_lshlrev_b64 v[80:81], s14, v[80:81]
	v_lshl_add_u64 v[80:81], v[80:81], 1, v[150:151]
	v_cvt_pk_bf16_f32 v78, v72, v73
	v_cvt_pk_bf16_f32 v79, v74, v75
	global_store_dwordx4 v[80:81], v[76:79], off
	v_cvt_pk_bf16_f32 v72, v68, v69
	s_waitcnt lgkmcnt(0)
	v_add_f32_e32 v68, v82, v83
	v_mov_b32_e32 v244, v68
	v_mov_b32_e32 v69, v68
	s_nop 1
	v_permlane32_swap_b32_e32 v244, v69
	v_cvt_pk_bf16_f32 v73, v70, v71
	v_cvt_pk_bf16_f32 v74, v64, v65
	v_cvt_pk_bf16_f32 v75, v66, v67
	global_store_dwordx4 v[80:81], v[72:75], off offset:256
	s_and_saveexec_b64 s[10:11], s[4:5]
	s_cbranch_execz .LBB0_210
	s_waitcnt lgkmcnt(0)
	v_add_f32_e32 v64, v68, v69
	global_atomic_add_f32 v[112:113], v64, off offset:192
.LBB0_210:
	s_or_b64 exec, exec, s[10:11]
	v_mul_f32_e32 v66, v61, v61
	v_mul_f32_e32 v67, v63, v63
	v_fmac_f32_e32 v66, v60, v60
	v_fmac_f32_e32 v67, v62, v62
	v_cvt_pk_bf16_f32 v60, v60, v61
	v_cvt_pk_bf16_f32 v61, v62, v63
	v_mul_f32_e32 v62, v53, v53
	v_mul_f32_e32 v63, v55, v55
	v_fmac_f32_e32 v62, v52, v52
	v_fmac_f32_e32 v63, v54, v54
	v_add_f32_e32 v66, v66, v67
	v_mul_f32_e32 v67, v57, v57
	v_add_f32_e32 v62, v62, v63
	v_mul_f32_e32 v63, v49, v49
	v_fmac_f32_e32 v67, v56, v56
	v_fmac_f32_e32 v63, v48, v48
	v_add_f32_e32 v66, v66, v67
	v_mul_f32_e32 v67, v59, v59
	v_add_f32_e32 v62, v62, v63
	v_mul_f32_e32 v63, v51, v51
	v_fmac_f32_e32 v67, v58, v58
	v_fmac_f32_e32 v63, v50, v50
	v_add_f32_e32 v66, v67, v66
	v_add_f32_e32 v62, v63, v62
	v_add_f32_e32 v66, v66, v62
	v_mov_b32_e32 v244, v66
	v_mov_b32_e32 v67, v66
	s_nop 1
	v_permlane16_swap_b32_e32 v244, v67
	v_add_u32_e32 v64, 0x80, v148
	v_ashrrev_i32_e32 v65, 31, v64
	v_lshlrev_b64 v[64:65], s14, v[64:65]
	v_lshl_add_u64 v[64:65], v[64:65], 1, v[150:151]
	v_cvt_pk_bf16_f32 v62, v56, v57
	v_cvt_pk_bf16_f32 v63, v58, v59
	global_store_dwordx4 v[64:65], v[60:63], off
	v_cvt_pk_bf16_f32 v56, v52, v53
	s_waitcnt lgkmcnt(0)
	v_add_f32_e32 v52, v66, v67
	v_mov_b32_e32 v244, v52
	v_mov_b32_e32 v53, v52
	s_nop 1
	v_permlane32_swap_b32_e32 v244, v53
	v_cvt_pk_bf16_f32 v57, v54, v55
	v_cvt_pk_bf16_f32 v58, v48, v49
	v_cvt_pk_bf16_f32 v59, v50, v51
	global_store_dwordx4 v[64:65], v[56:59], off offset:256
	s_and_saveexec_b64 s[10:11], s[4:5]
	s_cbranch_execz .LBB0_212
	s_waitcnt lgkmcnt(0)
	v_add_f32_e32 v48, v52, v53
	global_atomic_add_f32 v[112:113], v48, off offset:512
; __device__ __forceinline__ u32x4 pack8(f32x4 v0, f32x4 v1) { u32x4 w; w.x = cvt_pk_bf16(v0[0], v0[1]); w.y = cvt_pk_bf16(v0[2], v0[3]); w.z = cvt_pk_bf16(v1[0], v1[1]); w.w = cvt_pk_bf16(v1[2], v1[3]); return w; }
;     __device__ __forceinline__ void operator()(EPI_ARGS) const {
;     ...
;         if (pn <= 2) {
;             bf16_t* base = pn < 2 ? CQ : CKV; const int ld = pn < 2 ? 512 : 256, colt = pn < 2 ? pn * 256 : 0; float* rs = pn < 2 ? rsq_q : rsq_kv;
; #pragma unroll
;             for (int ai = 0; ai < 2; ++ai)
; #pragma unroll
;                 for (int m = 0; m < 4; ++m) { const int row = EPI_ROW(ai, m); float ss = 0.f;
; #pragma unroll
;                     for (int bj = 0; bj < 2; ++bj) { const f32x4 v0 = acc[ai][bj][m][0], v1 = acc[ai][bj][m][1];
;                         ss += (v0[0] * v0[0] + v0[1] * v0[1]) + (v0[2] * v0[2] + v0[3] * v0[3]) + (v1[0] * v1[0] + v1[1] * v1[1]) + (v1[2] * v1[2] + v1[3] * v1[3]);
;                         *(u32x4*)(base + (size_t)row * ld + colt + bj * 128 + wc * 32 + 8 * fq) = pack8(v0, v1); }
;                     ss += __shfl_xor(ss, 16); ss += __shfl_xor(ss, 32);
;                     if (fq == 0) atomicAdd(rs + row, ss); }
.LBB0_212:
	s_or_b64 exec, exec, s[10:11]
	v_mul_f32_e32 v50, v45, v45
	v_mul_f32_e32 v51, v47, v47
	v_fmac_f32_e32 v50, v44, v44
	v_fmac_f32_e32 v51, v46, v46
	v_cvt_pk_bf16_f32 v44, v44, v45
	v_cvt_pk_bf16_f32 v45, v46, v47
	v_mul_f32_e32 v46, v37, v37
	v_mul_f32_e32 v47, v39, v39
	v_fmac_f32_e32 v46, v36, v36
	v_fmac_f32_e32 v47, v38, v38
	v_add_f32_e32 v50, v50, v51
	v_mul_f32_e32 v51, v41, v41
	v_add_f32_e32 v46, v46, v47
	v_mul_f32_e32 v47, v33, v33
	v_fmac_f32_e32 v51, v40, v40
	v_fmac_f32_e32 v47, v32, v32
	v_add_f32_e32 v50, v50, v51
	v_mul_f32_e32 v51, v43, v43
	v_add_f32_e32 v46, v46, v47
	v_mul_f32_e32 v47, v35, v35
	v_fmac_f32_e32 v51, v42, v42
	v_fmac_f32_e32 v47, v34, v34
	v_add_f32_e32 v50, v51, v50
	v_add_f32_e32 v46, v47, v46
	v_add_f32_e32 v50, v50, v46
	v_mov_b32_e32 v244, v50
	v_mov_b32_e32 v51, v50
	s_nop 1
	v_permlane16_swap_b32_e32 v244, v51
	v_add_u32_e32 v48, 0x90, v148
	v_ashrrev_i32_e32 v49, 31, v48
	v_lshlrev_b64 v[48:49], s14, v[48:49]
	v_lshl_add_u64 v[48:49], v[48:49], 1, v[150:151]
	v_cvt_pk_bf16_f32 v46, v40, v41
	v_cvt_pk_bf16_f32 v47, v42, v43
	global_store_dwordx4 v[48:49], v[44:47], off
	v_cvt_pk_bf16_f32 v40, v36, v37
	s_waitcnt lgkmcnt(0)
	v_add_f32_e32 v36, v50, v51
	v_mov_b32_e32 v244, v36
	v_mov_b32_e32 v37, v36
	s_nop 1
	v_permlane32_swap_b32_e32 v244, v37
	v_cvt_pk_bf16_f32 v41, v38, v39
	v_cvt_pk_bf16_f32 v42, v32, v33
	v_cvt_pk_bf16_f32 v43, v34, v35
	global_store_dwordx4 v[48:49], v[40:43], off offset:256
	s_and_saveexec_b64 s[10:11], s[4:5]
	s_cbranch_execz .LBB0_214
	s_waitcnt lgkmcnt(0)
	v_add_f32_e32 v32, v36, v37
	global_atomic_add_f32 v[112:113], v32, off offset:576
.LBB0_214:
	s_or_b64 exec, exec, s[10:11]
	v_mul_f32_e32 v34, v29, v29
	v_mul_f32_e32 v35, v31, v31
	v_fmac_f32_e32 v34, v28, v28
	v_fmac_f32_e32 v35, v30, v30
	v_cvt_pk_bf16_f32 v28, v28, v29
	v_cvt_pk_bf16_f32 v29, v30, v31
	v_mul_f32_e32 v30, v21, v21
	v_mul_f32_e32 v31, v23, v23
	v_fmac_f32_e32 v30, v20, v20
	v_fmac_f32_e32 v31, v22, v22
	v_add_f32_e32 v34, v34, v35
	v_mul_f32_e32 v35, v25, v25
	v_add_f32_e32 v30, v30, v31
	v_mul_f32_e32 v31, v17, v17
	v_fmac_f32_e32 v35, v24, v24
	v_fmac_f32_e32 v31, v16, v16
	v_add_f32_e32 v34, v34, v35
	v_mul_f32_e32 v35, v27, v27
	v_add_f32_e32 v30, v30, v31
	v_mul_f32_e32 v31, v19, v19
	v_fmac_f32_e32 v35, v26, v26
	v_fmac_f32_e32 v31, v18, v18
	v_add_f32_e32 v34, v35, v34
	v_add_f32_e32 v30, v31, v30
	v_add_f32_e32 v34, v34, v30
	v_mov_b32_e32 v244, v34
	v_mov_b32_e32 v35, v34
	s_nop 1
	v_permlane16_swap_b32_e32 v244, v35
	v_add_u32_e32 v32, 0xa0, v148
	v_ashrrev_i32_e32 v33, 31, v32
	v_lshlrev_b64 v[32:33], s14, v[32:33]
	v_lshl_add_u64 v[32:33], v[32:33], 1, v[150:151]
	v_cvt_pk_bf16_f32 v30, v24, v25
	v_cvt_pk_bf16_f32 v31, v26, v27
	global_store_dwordx4 v[32:33], v[28:31], off
	v_cvt_pk_bf16_f32 v24, v20, v21
	s_waitcnt lgkmcnt(0)
	v_add_f32_e32 v20, v34, v35
	v_mov_b32_e32 v244, v20
	v_mov_b32_e32 v21, v20
	s_nop 1
	v_permlane32_swap_b32_e32 v244, v21
	v_cvt_pk_bf16_f32 v25, v22, v23
	v_cvt_pk_bf16_f32 v26, v16, v17
	v_cvt_pk_bf16_f32 v27, v18, v19
	global_store_dwordx4 v[32:33], v[24:27], off offset:256
	s_and_saveexec_b64 s[10:11], s[4:5]
	s_cbranch_execz .LBB0_216
	s_waitcnt lgkmcnt(0)
	v_add_f32_e32 v16, v20, v21
	global_atomic_add_f32 v[112:113], v16, off offset:640
.LBB0_216:
	s_or_b64 exec, exec, s[10:11]
	v_mul_f32_e32 v18, v13, v13
	v_mul_f32_e32 v19, v15, v15
	v_fmac_f32_e32 v18, v12, v12
	v_fmac_f32_e32 v19, v14, v14
	v_cvt_pk_bf16_f32 v12, v12, v13
	v_cvt_pk_bf16_f32 v13, v14, v15
	v_mul_f32_e32 v14, v5, v5
	v_mul_f32_e32 v15, v7, v7
	v_fmac_f32_e32 v14, v4, v4
	v_fmac_f32_e32 v15, v6, v6
	v_add_f32_e32 v18, v18, v19
	v_mul_f32_e32 v19, v9, v9
	v_add_f32_e32 v14, v14, v15
	v_mul_f32_e32 v15, v1, v1
	v_fmac_f32_e32 v19, v8, v8
	v_fmac_f32_e32 v15, v0, v0
	v_add_f32_e32 v18, v18, v19
	v_mul_f32_e32 v19, v11, v11
	v_add_f32_e32 v14, v14, v15
	v_mul_f32_e32 v15, v3, v3
	v_fmac_f32_e32 v19, v10, v10
	v_fmac_f32_e32 v15, v2, v2
	v_add_f32_e32 v18, v19, v18
	v_add_f32_e32 v14, v15, v14
	v_add_f32_e32 v18, v18, v14
	v_mov_b32_e32 v244, v18
	v_mov_b32_e32 v19, v18
	s_nop 1
	v_permlane16_swap_b32_e32 v244, v19
	v_add_u32_e32 v16, 0xb0, v148
	v_ashrrev_i32_e32 v17, 31, v16
	v_lshlrev_b64 v[16:17], s14, v[16:17]
	v_lshl_add_u64 v[16:17], v[16:17], 1, v[150:151]
	v_cvt_pk_bf16_f32 v14, v8, v9
	v_cvt_pk_bf16_f32 v15, v10, v11
	global_store_dwordx4 v[16:17], v[12:15], off
	v_cvt_pk_bf16_f32 v8, v4, v5
	s_waitcnt lgkmcnt(0)
	v_add_f32_e32 v4, v18, v19
	v_mov_b32_e32 v244, v4
	v_mov_b32_e32 v5, v4
	s_nop 1
	v_permlane32_swap_b32_e32 v244, v5
	v_cvt_pk_bf16_f32 v9, v6, v7
	v_cvt_pk_bf16_f32 v10, v0, v1
	v_cvt_pk_bf16_f32 v11, v2, v3
	global_store_dwordx4 v[16:17], v[8:11], off offset:256
	s_and_saveexec_b64 s[10:11], s[4:5]
	s_cbranch_execz .LBB0_218
	s_waitcnt lgkmcnt(0)
	v_add_f32_e32 v0, v4, v5
	global_atomic_add_f32 v[112:113], v0, off offset:704

; __device__ __forceinline__ u32x4 pack8(f32x4 v0, f32x4 v1) { u32x4 w; w.x = cvt_pk_bf16(v0[0], v0[1]); w.y = cvt_pk_bf16(v0[2], v0[3]); w.z = cvt_pk_bf16(v1[0], v1[1]); w.w = cvt_pk_bf16(v1[2], v1[3]); return w; }
; __device__ __forceinline__ float sigmoidf_(float x) { return __builtin_amdgcn_rcpf(1.f + __builtin_amdgcn_exp2f(-1.4426950408889634f * x)); }
;     __device__ __forceinline__ void operator()(EPI_ARGS) const {
;     ...
;         for (int bj = 0; bj < 2; ++bj) { const int col0 = EPI_COL(bj); const f32x4 b0 = *(const f32x4*)(bias + col0), b1 = *(const f32x4*)(bias + col0 + 4);
; #pragma unroll
;             for (int ai = 0; ai < 2; ++ai)
; #pragma unroll
;                 for (int m = 0; m < 4; ++m) { const int row = EPI_ROW(ai, m); const u32x4 yv = *(const u32x4*)(Y + (size_t)row * 1024 + col0);
;                     f32x4 v0 = acc[ai][bj][m][0] + b0, v1 = acc[ai][bj][m][1] + b1;
;                     v0[0] = __uint_as_float(yv.x << 16) * sigmoidf_(v0[0]); v0[1] = __uint_as_float(yv.x & 0xffff0000u) * sigmoidf_(v0[1]);
;                     v0[2] = __uint_as_float(yv.y << 16) * sigmoidf_(v0[2]); v0[3] = __uint_as_float(yv.y & 0xffff0000u) * sigmoidf_(v0[3]);
;                     v1[0] = __uint_as_float(yv.z << 16) * sigmoidf_(v1[0]); v1[1] = __uint_as_float(yv.z & 0xffff0000u) * sigmoidf_(v1[1]);
;                     v1[2] = __uint_as_float(yv.w << 16) * sigmoidf_(v1[2]); v1[3] = __uint_as_float(yv.w & 0xffff0000u) * sigmoidf_(v1[3]);
;                     *(u32x4*)(MIX + (size_t)row * 2048 + 1024 + col0) = pack8(v0, v1);
;                     float ss = (v0[0] * v0[0] + v0[1] * v0[1]) + (v0[2] * v0[2] + v0[3] * v0[3]) + (v1[0] * v1[0] + v1[1] * v1[1]) + (v1[2] * v1[2] + v1[3] * v1[3]);
;                     ss += __shfl_xor(ss, 16); ss += __shfl_xor(ss, 32);
;                     if (fq == 0) atomicAdd(rsq + row, ss); } }
.LBB0_599:
	v_lshl_or_b32 v142, s73, 8, v153
	v_lshl_add_u32 v146, s74, 8, v152
	v_readlane_b32 s68, v246, 25
	v_ashrrev_i32_e32 v143, 31, v142
	v_readlane_b32 s70, v246, 27
	v_readlane_b32 s71, v246, 28
	v_ashrrev_i32_e32 v147, 31, v146
	v_lshlrev_b64 v[144:145], 11, v[146:147]
	v_lshl_add_u64 v[140:141], v[142:143], 2, s[70:71]
	global_load_dwordx4 v[104:107], v[140:141], off offset:16
	global_load_dwordx4 v[108:111], v[140:141], off
	v_lshl_add_u64 v[166:167], s[88:89], 0, v[144:145]
	v_lshlrev_b64 v[144:145], 1, v[142:143]
	v_lshl_add_u64 v[142:143], v[166:167], 0, v[144:145]
	global_load_dwordx4 v[170:173], v[142:143], off
	v_readlane_b32 s69, v246, 26
	v_readlane_b32 s72, v246, 29
	v_readlane_b32 s73, v246, 30
	v_readlane_b32 s74, v246, 31
	v_readlane_b32 s75, v246, 32
	v_readlane_b32 s76, v246, 33
	v_readlane_b32 s77, v246, 34
	v_readlane_b32 s78, v246, 35
	v_readlane_b32 s79, v246, 36
	v_readlane_b32 s80, v246, 37
	v_readlane_b32 s81, v246, 38
	v_readlane_b32 s82, v246, 39
	v_readlane_b32 s83, v246, 40
	s_waitcnt vmcnt(2)
	v_pk_add_f32 v[128:129], v[128:129], v[104:105]
	s_waitcnt vmcnt(1)
	v_pk_add_f32 v[132:133], v[132:133], v[108:109]
	v_pk_add_f32 v[134:135], v[134:135], v[110:111]
	v_mul_f32_e32 v132, 0xbfb8aa3b, v132
	v_exp_f32_e32 v132, v132
	v_mul_f32_e32 v133, 0xbfb8aa3b, v133
	v_exp_f32_e32 v133, v133
	s_waitcnt vmcnt(0)
	v_lshlrev_b32_e32 v163, 16, v170
	v_add_f32_e32 v132, 1.0, v132
	v_rcp_f32_e32 v132, v132
	v_add_f32_e32 v133, 1.0, v133
	v_rcp_f32_e32 v133, v133
	v_mul_f32_e32 v128, 0xbfb8aa3b, v128
	v_mul_f32_e32 v163, v132, v163
	v_and_b32_e32 v132, 0xffff0000, v170
	v_mul_f32_e32 v165, v133, v132
	v_mul_f32_e32 v133, 0xbfb8aa3b, v134
	v_exp_f32_e32 v133, v133
	v_lshlrev_b32_e32 v132, 16, v171
	v_exp_f32_e32 v128, v128
	v_mul_f32_e32 v129, 0xbfb8aa3b, v129
	v_add_f32_e32 v133, 1.0, v133
	v_rcp_f32_e32 v133, v133
	v_exp_f32_e32 v129, v129
	v_add_f32_e32 v128, 1.0, v128
	v_rcp_f32_e32 v128, v128
	v_mul_f32_e32 v134, v133, v132
	v_mul_f32_e32 v133, 0xbfb8aa3b, v135
	v_exp_f32_e32 v133, v133
	v_add_f32_e32 v129, 1.0, v129
	v_rcp_f32_e32 v129, v129
	v_and_b32_e32 v132, 0xffff0000, v171
	v_add_f32_e32 v133, 1.0, v133
	v_rcp_f32_e32 v133, v133
	v_pk_add_f32 v[130:131], v[130:131], v[106:107]
	v_mul_f32_e32 v135, v133, v132
	v_lshlrev_b32_e32 v132, 16, v172
	v_mul_f32_e32 v166, v128, v132
	v_and_b32_e32 v128, 0xffff0000, v172
	v_mul_f32_e32 v167, v129, v128
	v_mul_f32_e32 v129, 0xbfb8aa3b, v130
	v_exp_f32_e32 v129, v129
	v_lshlrev_b32_e32 v128, 16, v173
	v_cvt_pk_bf16_f32 v130, v163, v165
	v_add_f32_e32 v129, 1.0, v129
	v_rcp_f32_e32 v129, v129
	s_nop 0
	v_mul_f32_e32 v170, v129, v128
	v_mul_f32_e32 v129, 0xbfb8aa3b, v131
	v_exp_f32_e32 v129, v129
	v_and_b32_e32 v128, 0xffff0000, v173
	v_cvt_pk_bf16_f32 v131, v134, v135
	v_cvt_pk_bf16_f32 v132, v166, v167
	v_add_f32_e32 v129, 1.0, v129
	v_rcp_f32_e32 v129, v129
	s_nop 0
	v_mul_f32_e32 v171, v129, v128
	v_lshlrev_b64 v[128:129], 12, v[146:147]
	v_lshl_add_u64 v[128:129], s[58:59], 0, v[128:129]
	v_lshl_add_u64 v[128:129], v[128:129], 0, v[144:145]
	v_cvt_pk_bf16_f32 v133, v170, v171
	global_store_dwordx4 v[128:129], v[130:133], off offset:2048
	s_nop 1
	v_mul_f32_e32 v130, v165, v165
	v_mul_f32_e32 v131, v135, v135
	v_fmac_f32_e32 v130, v163, v163
	v_fmac_f32_e32 v131, v134, v134
	v_add_f32_e32 v130, v130, v131
	v_mul_f32_e32 v131, v167, v167
	v_fmac_f32_e32 v131, v166, v166
	v_add_f32_e32 v130, v130, v131
	v_mul_f32_e32 v131, v171, v171
	v_fmac_f32_e32 v131, v170, v170
	v_and_b32_e32 v132, 64, v161
	v_add_f32_e32 v130, v131, v130
	v_xor_b32_e32 v131, 16, v161
	v_add_u32_e32 v133, 64, v132
	v_cmp_lt_i32_e32 vcc, v131, v133
	s_nop 1
	v_cndmask_b32_e32 v131, v161, v131, vcc
	v_lshlrev_b32_e32 v134, 2, v131
	v_mov_b32_e32 v244, v130
	v_mov_b32_e32 v131, v130
	s_nop 1
	v_permlane16_swap_b32_e32 v244, v131
	s_waitcnt lgkmcnt(0)
	v_add_f32_e32 v132, v130, v131
	v_xor_b32_e32 v130, 32, v161
	v_cmp_lt_i32_e32 vcc, v130, v133
	s_nop 1
	v_cndmask_b32_e32 v130, v161, v130, vcc
	v_lshlrev_b32_e32 v135, 2, v130
	v_mov_b32_e32 v244, v132
	v_mov_b32_e32 v133, v132
	s_nop 1
	v_permlane32_swap_b32_e32 v244, v133
	v_lshl_add_u64 v[130:131], v[146:147], 2, s[64:65]
	s_waitcnt lgkmcnt(0)
	v_add_f32_e32 v176, v132, v133
	v_mov_b32_e32 v178, v130
	v_mov_b32_e32 v179, v131
	v_or_b32_e32 v166, 16, v146
	v_ashrrev_i32_e32 v167, 31, v166
	s_waitcnt lgkmcnt(0)
	v_lshlrev_b64 v[132:133], 11, v[166:167]
	v_lshl_add_u64 v[132:133], s[88:89], 0, v[132:133]
	v_lshl_add_u64 v[132:133], v[132:133], 0, v[144:145]
	global_load_dwordx4 v[170:173], v[132:133], off
	s_and_saveexec_b64 s[10:11], s[4:5]
	global_atomic_add_f32 v[178:179], v176, off
	s_mov_b64 exec, s[10:11]
	v_pk_add_f32 v[126:127], v[126:127], v[110:111]
	v_pk_add_f32 v[124:125], v[124:125], v[108:109]
	v_pk_add_f32 v[120:121], v[120:121], v[104:105]
	v_mul_f32_e32 v125, 0xbfb8aa3b, v125
	v_mul_f32_e32 v127, 0xbfb8aa3b, v127
	v_pk_add_f32 v[122:123], v[122:123], v[106:107]
	v_mul_f32_e32 v124, 0xbfb8aa3b, v124
	v_mul_f32_e32 v126, 0xbfb8aa3b, v126
	v_mul_f32_e32 v121, 0xbfb8aa3b, v121
	v_exp_f32_e32 v125, v125
	v_exp_f32_e32 v127, v127
	v_mul_f32_e32 v120, 0xbfb8aa3b, v120
	v_mul_f32_e32 v123, 0xbfb8aa3b, v123
	v_exp_f32_e32 v124, v124
	v_exp_f32_e32 v126, v126
	v_exp_f32_e32 v121, v121
	v_mul_f32_e32 v122, 0xbfb8aa3b, v122
	v_exp_f32_e32 v120, v120
	v_exp_f32_e32 v123, v123
	v_exp_f32_e32 v122, v122
	v_add_f32_e32 v125, 1.0, v125
	v_add_f32_e32 v127, 1.0, v127
	v_add_f32_e32 v124, 1.0, v124
	v_add_f32_e32 v126, 1.0, v126
	v_add_f32_e32 v121, 1.0, v121
	v_rcp_f32_e32 v125, v125
	v_rcp_f32_e32 v127, v127
	v_add_f32_e32 v120, 1.0, v120
	v_add_f32_e32 v123, 1.0, v123
	v_rcp_f32_e32 v124, v124
	v_rcp_f32_e32 v126, v126
	v_rcp_f32_e32 v121, v121
	v_add_f32_e32 v122, 1.0, v122
	v_rcp_f32_e32 v120, v120
	v_rcp_f32_e32 v123, v123
	v_rcp_f32_e32 v122, v122
	s_waitcnt vmcnt(1)
; __device__ __forceinline__ u32x4 pack8(f32x4 v0, f32x4 v1) { u32x4 w; w.x = cvt_pk_bf16(v0[0], v0[1]); w.y = cvt_pk_bf16(v0[2], v0[3]); w.z = cvt_pk_bf16(v1[0], v1[1]); w.w = cvt_pk_bf16(v1[2], v1[3]); return w; }
; __device__ __forceinline__ float sigmoidf_(float x) { return __builtin_amdgcn_rcpf(1.f + __builtin_amdgcn_exp2f(-1.4426950408889634f * x)); }
;     __device__ __forceinline__ void operator()(EPI_ARGS) const {
;     ...
;         for (int bj = 0; bj < 2; ++bj) { const int col0 = EPI_COL(bj); const f32x4 b0 = *(const f32x4*)(bias + col0), b1 = *(const f32x4*)(bias + col0 + 4);
; #pragma unroll
;             for (int ai = 0; ai < 2; ++ai)
; #pragma unroll
;                 for (int m = 0; m < 4; ++m) { const int row = EPI_ROW(ai, m); const u32x4 yv = *(const u32x4*)(Y + (size_t)row * 1024 + col0);
;                     f32x4 v0 = acc[ai][bj][m][0] + b0, v1 = acc[ai][bj][m][1] + b1;
;                     v0[0] = __uint_as_float(yv.x << 16) * sigmoidf_(v0[0]); v0[1] = __uint_as_float(yv.x & 0xffff0000u) * sigmoidf_(v0[1]);
;                     v0[2] = __uint_as_float(yv.y << 16) * sigmoidf_(v0[2]); v0[3] = __uint_as_float(yv.y & 0xffff0000u) * sigmoidf_(v0[3]);
;                     v1[0] = __uint_as_float(yv.z << 16) * sigmoidf_(v1[0]); v1[1] = __uint_as_float(yv.z & 0xffff0000u) * sigmoidf_(v1[1]);
;                     v1[2] = __uint_as_float(yv.w << 16) * sigmoidf_(v1[2]); v1[3] = __uint_as_float(yv.w & 0xffff0000u) * sigmoidf_(v1[3]);
;                     *(u32x4*)(MIX + (size_t)row * 2048 + 1024 + col0) = pack8(v0, v1);
;                     float ss = (v0[0] * v0[0] + v0[1] * v0[1]) + (v0[2] * v0[2] + v0[3] * v0[3]) + (v1[0] * v1[0] + v1[1] * v1[1]) + (v1[2] * v1[2] + v1[3] * v1[3]);
;                     ss += __shfl_xor(ss, 16); ss += __shfl_xor(ss, 32);
;                     if (fq == 0) atomicAdd(rsq + row, ss); } }
	v_lshlrev_b32_e32 v147, 16, v170
	v_and_b32_e32 v163, 0xffff0000, v170
	v_and_b32_e32 v170, 0xffff0000, v171
	v_lshlrev_b32_e32 v165, 16, v171
	v_lshlrev_b32_e32 v171, 16, v172
	v_and_b32_e32 v172, 0xffff0000, v172
	v_mul_f32_e32 v125, v125, v163
	v_mul_f32_e32 v127, v127, v170
	v_lshlrev_b32_e32 v174, 16, v173
	v_and_b32_e32 v173, 0xffff0000, v173
	v_mul_f32_e32 v124, v124, v147
	v_mul_f32_e32 v126, v126, v165
	v_mul_f32_e32 v121, v121, v172
	v_cvt_pk_bf16_f32 v170, v124, v125
	v_mul_f32_e32 v125, v125, v125
	v_mul_f32_e32 v147, v127, v127
	v_mul_f32_e32 v120, v120, v171
	v_mul_f32_e32 v123, v123, v173
	v_mul_f32_e32 v163, v121, v121
	v_fmac_f32_e32 v125, v124, v124
	v_fmac_f32_e32 v147, v126, v126
	v_mul_f32_e32 v122, v122, v174
	v_mul_f32_e32 v165, v123, v123
	v_fmac_f32_e32 v163, v120, v120
	v_add_f32_e32 v124, v125, v147
	v_add_f32_e32 v124, v163, v124
	v_fmac_f32_e32 v165, v122, v122
	v_add_f32_e32 v124, v165, v124
	v_mov_b32_e32 v244, v124
	v_mov_b32_e32 v125, v124
	s_nop 1
	v_permlane16_swap_b32_e32 v244, v125
	v_cvt_pk_bf16_f32 v171, v126, v127
	v_cvt_pk_bf16_f32 v172, v120, v121
	v_lshlrev_b64 v[120:121], 12, v[166:167]
	v_lshl_add_u64 v[120:121], s[58:59], 0, v[120:121]
	s_waitcnt lgkmcnt(0)
	v_add_f32_e32 v124, v124, v125
	v_mov_b32_e32 v244, v124
	v_mov_b32_e32 v125, v124
	s_nop 1
	v_permlane32_swap_b32_e32 v244, v125
	v_cvt_pk_bf16_f32 v173, v122, v123
	v_lshl_add_u64 v[122:123], v[120:121], 0, v[144:145]
	v_lshl_add_u64 v[120:121], v[166:167], 2, s[64:65]
	global_store_dwordx4 v[122:123], v[170:173], off offset:2048
	s_waitcnt lgkmcnt(0)
	v_add_f32_e32 v176, v124, v125
	v_mov_b32_e32 v178, v120
	v_mov_b32_e32 v179, v121
	v_or_b32_e32 v126, 32, v146
	v_ashrrev_i32_e32 v127, 31, v126
	s_waitcnt lgkmcnt(0)
	v_lshlrev_b64 v[124:125], 11, v[126:127]
	v_lshl_add_u64 v[124:125], s[88:89], 0, v[124:125]
	v_lshl_add_u64 v[124:125], v[124:125], 0, v[144:145]
	global_load_dwordx4 v[170:173], v[124:125], off
	s_and_saveexec_b64 s[10:11], s[4:5]
	global_atomic_add_f32 v[178:179], v176, off
	s_mov_b64 exec, s[10:11]
	v_pk_add_f32 v[118:119], v[118:119], v[110:111]
	v_pk_add_f32 v[116:117], v[116:117], v[108:109]
	v_pk_add_f32 v[112:113], v[112:113], v[104:105]
	v_mul_f32_e32 v117, 0xbfb8aa3b, v117
	v_mul_f32_e32 v119, 0xbfb8aa3b, v119
	v_pk_add_f32 v[114:115], v[114:115], v[106:107]
	v_mul_f32_e32 v116, 0xbfb8aa3b, v116
	v_mul_f32_e32 v118, 0xbfb8aa3b, v118
	v_mul_f32_e32 v113, 0xbfb8aa3b, v113
	v_exp_f32_e32 v117, v117
	v_exp_f32_e32 v119, v119
	v_mul_f32_e32 v112, 0xbfb8aa3b, v112
	v_mul_f32_e32 v115, 0xbfb8aa3b, v115
	v_exp_f32_e32 v116, v116
	v_exp_f32_e32 v118, v118
	v_exp_f32_e32 v113, v113
	v_mul_f32_e32 v114, 0xbfb8aa3b, v114
	v_exp_f32_e32 v112, v112
	v_exp_f32_e32 v115, v115
	v_exp_f32_e32 v114, v114
	v_add_f32_e32 v117, 1.0, v117
	v_add_f32_e32 v119, 1.0, v119
	v_add_f32_e32 v116, 1.0, v116
	v_add_f32_e32 v118, 1.0, v118
	v_add_f32_e32 v113, 1.0, v113
	v_rcp_f32_e32 v117, v117
	v_rcp_f32_e32 v119, v119
	v_add_f32_e32 v112, 1.0, v112
	v_add_f32_e32 v115, 1.0, v115
	v_rcp_f32_e32 v116, v116
	v_rcp_f32_e32 v118, v118
	v_rcp_f32_e32 v113, v113
	v_add_f32_e32 v114, 1.0, v114
	v_rcp_f32_e32 v112, v112
	v_rcp_f32_e32 v115, v115
	v_rcp_f32_e32 v114, v114
	s_waitcnt vmcnt(1)
	v_and_b32_e32 v163, 0xffff0000, v170
	v_and_b32_e32 v166, 0xffff0000, v171
	v_lshlrev_b32_e32 v147, 16, v170
	v_lshlrev_b32_e32 v165, 16, v171
	v_and_b32_e32 v170, 0xffff0000, v172
	v_mul_f32_e32 v117, v117, v163
	v_mul_f32_e32 v119, v119, v166
	v_lshlrev_b32_e32 v167, 16, v172
	v_and_b32_e32 v172, 0xffff0000, v173
	v_mul_f32_e32 v116, v116, v147
	v_mul_f32_e32 v118, v118, v165
	v_mul_f32_e32 v113, v113, v170
	v_cvt_pk_bf16_f32 v170, v116, v117
	v_mul_f32_e32 v117, v117, v117
	v_mul_f32_e32 v147, v119, v119
	v_lshlrev_b32_e32 v171, 16, v173
	v_mul_f32_e32 v112, v112, v167
	v_mul_f32_e32 v115, v115, v172
	v_mul_f32_e32 v163, v113, v113
	v_fmac_f32_e32 v117, v116, v116
	v_fmac_f32_e32 v147, v118, v118
	v_mul_f32_e32 v114, v114, v171
	v_mul_f32_e32 v165, v115, v115
	v_fmac_f32_e32 v163, v112, v112
	v_add_f32_e32 v116, v117, v147
	v_add_f32_e32 v116, v163, v116
	v_fmac_f32_e32 v165, v114, v114
	v_add_f32_e32 v116, v165, v116
	v_mov_b32_e32 v244, v116
	v_mov_b32_e32 v117, v116
	s_nop 1
	v_permlane16_swap_b32_e32 v244, v117
	v_cvt_pk_bf16_f32 v171, v118, v119
	v_cvt_pk_bf16_f32 v172, v112, v113
	v_lshlrev_b64 v[112:113], 12, v[126:127]
	v_lshl_add_u64 v[112:113], s[58:59], 0, v[112:113]
	s_waitcnt lgkmcnt(0)
	v_add_f32_e32 v116, v116, v117
	v_mov_b32_e32 v244, v116
	v_mov_b32_e32 v117, v116
	s_nop 1
	v_permlane32_swap_b32_e32 v244, v117
	v_cvt_pk_bf16_f32 v173, v114, v115
	v_lshl_add_u64 v[114:115], v[112:113], 0, v[144:145]
	v_lshl_add_u64 v[112:113], v[126:127], 2, s[64:65]
	global_store_dwordx4 v[114:115], v[170:173], off offset:2048
	s_mov_b64 s[76:77], s[92:93]
	s_mov_b64 s[78:79], s[94:95]
	s_waitcnt lgkmcnt(0)
	v_add_f32_e32 v176, v116, v117
	v_mov_b32_e32 v178, v112
	v_mov_b32_e32 v179, v113
	v_or_b32_e32 v118, 48, v146
	v_ashrrev_i32_e32 v119, 31, v118
	s_waitcnt lgkmcnt(0)
; __device__ __forceinline__ u32x4 pack8(f32x4 v0, f32x4 v1) { u32x4 w; w.x = cvt_pk_bf16(v0[0], v0[1]); w.y = cvt_pk_bf16(v0[2], v0[3]); w.z = cvt_pk_bf16(v1[0], v1[1]); w.w = cvt_pk_bf16(v1[2], v1[3]); return w; }
; __device__ __forceinline__ float sigmoidf_(float x) { return __builtin_amdgcn_rcpf(1.f + __builtin_amdgcn_exp2f(-1.4426950408889634f * x)); }
;     __device__ __forceinline__ void operator()(EPI_ARGS) const {
;     ...
;         for (int bj = 0; bj < 2; ++bj) { const int col0 = EPI_COL(bj); const f32x4 b0 = *(const f32x4*)(bias + col0), b1 = *(const f32x4*)(bias + col0 + 4);
; #pragma unroll
;             for (int ai = 0; ai < 2; ++ai)
; #pragma unroll
;                 for (int m = 0; m < 4; ++m) { const int row = EPI_ROW(ai, m); const u32x4 yv = *(const u32x4*)(Y + (size_t)row * 1024 + col0);
;                     f32x4 v0 = acc[ai][bj][m][0] + b0, v1 = acc[ai][bj][m][1] + b1;
;                     v0[0] = __uint_as_float(yv.x << 16) * sigmoidf_(v0[0]); v0[1] = __uint_as_float(yv.x & 0xffff0000u) * sigmoidf_(v0[1]);
;                     v0[2] = __uint_as_float(yv.y << 16) * sigmoidf_(v0[2]); v0[3] = __uint_as_float(yv.y & 0xffff0000u) * sigmoidf_(v0[3]);
;                     v1[0] = __uint_as_float(yv.z << 16) * sigmoidf_(v1[0]); v1[1] = __uint_as_float(yv.z & 0xffff0000u) * sigmoidf_(v1[1]);
;                     v1[2] = __uint_as_float(yv.w << 16) * sigmoidf_(v1[2]); v1[3] = __uint_as_float(yv.w & 0xffff0000u) * sigmoidf_(v1[3]);
;                     *(u32x4*)(MIX + (size_t)row * 2048 + 1024 + col0) = pack8(v0, v1);
;                     float ss = (v0[0] * v0[0] + v0[1] * v0[1]) + (v0[2] * v0[2] + v0[3] * v0[3]) + (v1[0] * v1[0] + v1[1] * v1[1]) + (v1[2] * v1[2] + v1[3] * v1[3]);
;                     ss += __shfl_xor(ss, 16); ss += __shfl_xor(ss, 32);
;                     if (fq == 0) atomicAdd(rsq + row, ss); } }
	v_lshlrev_b64 v[116:117], 11, v[118:119]
	v_lshl_add_u64 v[116:117], s[88:89], 0, v[116:117]
	v_lshl_add_u64 v[116:117], v[116:117], 0, v[144:145]
	global_load_dwordx4 v[170:173], v[116:117], off
	s_and_saveexec_b64 s[10:11], s[4:5]
	global_atomic_add_f32 v[178:179], v176, off
	s_mov_b64 exec, s[10:11]
	v_pk_add_f32 v[102:103], v[102:103], v[110:111]
	v_pk_add_f32 v[100:101], v[100:101], v[108:109]
	v_pk_add_f32 v[98:99], v[98:99], v[106:107]
	v_pk_add_f32 v[96:97], v[96:97], v[104:105]
	v_mul_f32_e32 v101, 0xbfb8aa3b, v101
	v_mul_f32_e32 v103, 0xbfb8aa3b, v103
	v_mul_f32_e32 v100, 0xbfb8aa3b, v100
	v_mul_f32_e32 v102, 0xbfb8aa3b, v102
	v_mul_f32_e32 v97, 0xbfb8aa3b, v97
	v_mul_f32_e32 v99, 0xbfb8aa3b, v99
	v_exp_f32_e32 v101, v101
	v_exp_f32_e32 v103, v103
	v_mul_f32_e32 v96, 0xbfb8aa3b, v96
	v_exp_f32_e32 v100, v100
	v_exp_f32_e32 v102, v102
	v_exp_f32_e32 v97, v97
	v_exp_f32_e32 v99, v99
	v_mul_f32_e32 v98, 0xbfb8aa3b, v98
	v_exp_f32_e32 v96, v96
	v_exp_f32_e32 v98, v98
	v_add_f32_e32 v101, 1.0, v101
	v_add_f32_e32 v103, 1.0, v103
	v_add_f32_e32 v100, 1.0, v100
	v_add_f32_e32 v102, 1.0, v102
	v_add_f32_e32 v97, 1.0, v97
	v_add_f32_e32 v99, 1.0, v99
	v_rcp_f32_e32 v101, v101
	v_rcp_f32_e32 v103, v103
	v_add_f32_e32 v96, 1.0, v96
	v_rcp_f32_e32 v100, v100
	v_rcp_f32_e32 v102, v102
	v_rcp_f32_e32 v97, v97
	v_rcp_f32_e32 v99, v99
	v_add_f32_e32 v98, 1.0, v98
	v_rcp_f32_e32 v96, v96
	v_rcp_f32_e32 v98, v98
	s_waitcnt vmcnt(1)
	v_and_b32_e32 v127, 0xffff0000, v170
	v_and_b32_e32 v163, 0xffff0000, v171
	v_lshlrev_b32_e32 v126, 16, v170
	v_lshlrev_b32_e32 v147, 16, v171
	v_and_b32_e32 v166, 0xffff0000, v172
	v_and_b32_e32 v170, 0xffff0000, v173
	v_mul_f32_e32 v101, v101, v127
	v_mul_f32_e32 v103, v103, v163
	v_lshlrev_b32_e32 v165, 16, v172
	v_mul_f32_e32 v100, v100, v126
	v_mul_f32_e32 v102, v102, v147
	v_mul_f32_e32 v97, v97, v166
	v_mul_f32_e32 v99, v99, v170
	v_cvt_pk_bf16_f32 v170, v100, v101
	v_mul_f32_e32 v101, v101, v101
	v_mul_f32_e32 v126, v103, v103
	v_lshlrev_b32_e32 v167, 16, v173
	v_mul_f32_e32 v96, v96, v165
	v_mul_f32_e32 v127, v97, v97
	v_fmac_f32_e32 v101, v100, v100
	v_fmac_f32_e32 v126, v102, v102
	v_mul_f32_e32 v98, v98, v167
	v_mul_f32_e32 v147, v99, v99
	v_fmac_f32_e32 v127, v96, v96
	v_add_f32_e32 v100, v101, v126
	v_add_f32_e32 v100, v127, v100
	v_fmac_f32_e32 v147, v98, v98
	v_add_f32_e32 v100, v147, v100
	v_mov_b32_e32 v244, v100
	v_mov_b32_e32 v101, v100
	s_nop 1
	v_permlane16_swap_b32_e32 v244, v101
	v_cvt_pk_bf16_f32 v171, v102, v103
	v_cvt_pk_bf16_f32 v172, v96, v97
	v_lshlrev_b64 v[96:97], 12, v[118:119]
	v_lshl_add_u64 v[96:97], s[58:59], 0, v[96:97]
	s_waitcnt lgkmcnt(0)
	v_add_f32_e32 v100, v100, v101
	v_mov_b32_e32 v244, v100
	v_mov_b32_e32 v101, v100
	s_nop 1
	v_permlane32_swap_b32_e32 v244, v101
	v_cvt_pk_bf16_f32 v173, v98, v99
	v_lshl_add_u64 v[98:99], v[96:97], 0, v[144:145]
	v_lshl_add_u64 v[96:97], v[118:119], 2, s[64:65]
	global_store_dwordx4 v[98:99], v[170:173], off offset:2048
	s_waitcnt lgkmcnt(0)
	v_add_f32_e32 v176, v100, v101
	v_mov_b32_e32 v178, v96
	v_mov_b32_e32 v179, v97
	v_add_u32_e32 v102, 0x80, v146
	v_ashrrev_i32_e32 v103, 31, v102
	s_waitcnt lgkmcnt(0)
	v_lshlrev_b64 v[100:101], 11, v[102:103]
	v_lshl_add_u64 v[100:101], s[88:89], 0, v[100:101]
	v_lshl_add_u64 v[100:101], v[100:101], 0, v[144:145]
	global_load_dwordx4 v[170:173], v[100:101], off
	s_and_saveexec_b64 s[10:11], s[4:5]
	global_atomic_add_f32 v[178:179], v176, off
	s_mov_b64 exec, s[10:11]
	v_pk_add_f32 v[94:95], v[94:95], v[110:111]
	v_pk_add_f32 v[92:93], v[92:93], v[108:109]
	v_pk_add_f32 v[88:89], v[88:89], v[104:105]
	v_mul_f32_e32 v93, 0xbfb8aa3b, v93
	v_mul_f32_e32 v95, 0xbfb8aa3b, v95
	v_pk_add_f32 v[90:91], v[90:91], v[106:107]
	v_mul_f32_e32 v92, 0xbfb8aa3b, v92
	v_mul_f32_e32 v94, 0xbfb8aa3b, v94
	v_mul_f32_e32 v89, 0xbfb8aa3b, v89
	v_exp_f32_e32 v93, v93
	v_exp_f32_e32 v95, v95
	v_mul_f32_e32 v88, 0xbfb8aa3b, v88
	v_mul_f32_e32 v91, 0xbfb8aa3b, v91
	v_exp_f32_e32 v92, v92
	v_exp_f32_e32 v94, v94
	v_exp_f32_e32 v89, v89
	v_mul_f32_e32 v90, 0xbfb8aa3b, v90
	v_exp_f32_e32 v88, v88
	v_exp_f32_e32 v91, v91
	v_exp_f32_e32 v90, v90
	v_add_f32_e32 v93, 1.0, v93
	v_add_f32_e32 v95, 1.0, v95
	v_add_f32_e32 v92, 1.0, v92
	v_add_f32_e32 v94, 1.0, v94
	v_add_f32_e32 v89, 1.0, v89
	v_rcp_f32_e32 v93, v93
	v_rcp_f32_e32 v95, v95
	v_add_f32_e32 v88, 1.0, v88
	v_add_f32_e32 v91, 1.0, v91
	v_rcp_f32_e32 v92, v92
	v_rcp_f32_e32 v94, v94
	v_rcp_f32_e32 v89, v89
	v_add_f32_e32 v90, 1.0, v90
	v_rcp_f32_e32 v88, v88
	v_rcp_f32_e32 v91, v91
	v_rcp_f32_e32 v90, v90
	s_waitcnt vmcnt(1)
	v_and_b32_e32 v119, 0xffff0000, v170
	v_and_b32_e32 v127, 0xffff0000, v171
	v_lshlrev_b32_e32 v118, 16, v170
	v_lshlrev_b32_e32 v126, 16, v171
	v_and_b32_e32 v163, 0xffff0000, v172
	v_mul_f32_e32 v93, v93, v119
	v_mul_f32_e32 v95, v95, v127
	v_lshlrev_b32_e32 v147, 16, v172
	v_and_b32_e32 v166, 0xffff0000, v173
	v_mul_f32_e32 v92, v92, v118
	v_mul_f32_e32 v94, v94, v126
	v_mul_f32_e32 v89, v89, v163
	v_cvt_pk_bf16_f32 v170, v92, v93
	v_mul_f32_e32 v93, v93, v93
	v_mul_f32_e32 v118, v95, v95
	v_lshlrev_b32_e32 v165, 16, v173
	v_mul_f32_e32 v88, v88, v147
	v_mul_f32_e32 v91, v91, v166
	v_mul_f32_e32 v119, v89, v89
	v_fmac_f32_e32 v93, v92, v92
	v_fmac_f32_e32 v118, v94, v94
	v_mul_f32_e32 v90, v90, v165
	v_mul_f32_e32 v126, v91, v91
	v_fmac_f32_e32 v119, v88, v88
	v_add_f32_e32 v92, v93, v118
	v_add_f32_e32 v92, v119, v92
	v_fmac_f32_e32 v126, v90, v90
	v_add_f32_e32 v92, v126, v92
	v_mov_b32_e32 v244, v92
	v_mov_b32_e32 v93, v92
	s_nop 1
	v_permlane16_swap_b32_e32 v244, v93
	v_cvt_pk_bf16_f32 v171, v94, v95
	v_cvt_pk_bf16_f32 v172, v88, v89
	v_lshlrev_b64 v[88:89], 12, v[102:103]
	v_lshl_add_u64 v[88:89], s[58:59], 0, v[88:89]
	s_waitcnt lgkmcnt(0)
; __device__ __forceinline__ u32x4 pack8(f32x4 v0, f32x4 v1) { u32x4 w; w.x = cvt_pk_bf16(v0[0], v0[1]); w.y = cvt_pk_bf16(v0[2], v0[3]); w.z = cvt_pk_bf16(v1[0], v1[1]); w.w = cvt_pk_bf16(v1[2], v1[3]); return w; }
; __device__ __forceinline__ float sigmoidf_(float x) { return __builtin_amdgcn_rcpf(1.f + __builtin_amdgcn_exp2f(-1.4426950408889634f * x)); }
;     __device__ __forceinline__ void operator()(EPI_ARGS) const {
;     ...
;         for (int bj = 0; bj < 2; ++bj) { const int col0 = EPI_COL(bj); const f32x4 b0 = *(const f32x4*)(bias + col0), b1 = *(const f32x4*)(bias + col0 + 4);
; #pragma unroll
;             for (int ai = 0; ai < 2; ++ai)
; #pragma unroll
;                 for (int m = 0; m < 4; ++m) { const int row = EPI_ROW(ai, m); const u32x4 yv = *(const u32x4*)(Y + (size_t)row * 1024 + col0);
;                     f32x4 v0 = acc[ai][bj][m][0] + b0, v1 = acc[ai][bj][m][1] + b1;
;                     v0[0] = __uint_as_float(yv.x << 16) * sigmoidf_(v0[0]); v0[1] = __uint_as_float(yv.x & 0xffff0000u) * sigmoidf_(v0[1]);
;                     v0[2] = __uint_as_float(yv.y << 16) * sigmoidf_(v0[2]); v0[3] = __uint_as_float(yv.y & 0xffff0000u) * sigmoidf_(v0[3]);
;                     v1[0] = __uint_as_float(yv.z << 16) * sigmoidf_(v1[0]); v1[1] = __uint_as_float(yv.z & 0xffff0000u) * sigmoidf_(v1[1]);
;                     v1[2] = __uint_as_float(yv.w << 16) * sigmoidf_(v1[2]); v1[3] = __uint_as_float(yv.w & 0xffff0000u) * sigmoidf_(v1[3]);
;                     *(u32x4*)(MIX + (size_t)row * 2048 + 1024 + col0) = pack8(v0, v1);
;                     float ss = (v0[0] * v0[0] + v0[1] * v0[1]) + (v0[2] * v0[2] + v0[3] * v0[3]) + (v1[0] * v1[0] + v1[1] * v1[1]) + (v1[2] * v1[2] + v1[3] * v1[3]);
;                     ss += __shfl_xor(ss, 16); ss += __shfl_xor(ss, 32);
;                     if (fq == 0) atomicAdd(rsq + row, ss); } }
	v_add_f32_e32 v92, v92, v93
	v_mov_b32_e32 v244, v92
	v_mov_b32_e32 v93, v92
	s_nop 1
	v_permlane32_swap_b32_e32 v244, v93
	v_cvt_pk_bf16_f32 v173, v90, v91
	v_lshl_add_u64 v[90:91], v[88:89], 0, v[144:145]
	v_lshl_add_u64 v[88:89], v[102:103], 2, s[64:65]
	global_store_dwordx4 v[90:91], v[170:173], off offset:2048
	s_waitcnt lgkmcnt(0)
	v_add_f32_e32 v176, v92, v93
	v_mov_b32_e32 v178, v88
	v_mov_b32_e32 v179, v89
	v_add_u32_e32 v94, 0x90, v146
	v_ashrrev_i32_e32 v95, 31, v94
	s_waitcnt lgkmcnt(0)
	v_lshlrev_b64 v[92:93], 11, v[94:95]
	v_lshl_add_u64 v[92:93], s[88:89], 0, v[92:93]
	v_lshl_add_u64 v[92:93], v[92:93], 0, v[144:145]
	global_load_dwordx4 v[170:173], v[92:93], off
	s_and_saveexec_b64 s[10:11], s[4:5]
	global_atomic_add_f32 v[178:179], v176, off
	s_mov_b64 exec, s[10:11]
	v_pk_add_f32 v[86:87], v[86:87], v[110:111]
	v_pk_add_f32 v[84:85], v[84:85], v[108:109]
	v_pk_add_f32 v[80:81], v[80:81], v[104:105]
	v_mul_f32_e32 v85, 0xbfb8aa3b, v85
	v_mul_f32_e32 v87, 0xbfb8aa3b, v87
	v_pk_add_f32 v[82:83], v[82:83], v[106:107]
	v_mul_f32_e32 v84, 0xbfb8aa3b, v84
	v_mul_f32_e32 v86, 0xbfb8aa3b, v86
	v_mul_f32_e32 v81, 0xbfb8aa3b, v81
	v_exp_f32_e32 v85, v85
	v_exp_f32_e32 v87, v87
	v_mul_f32_e32 v80, 0xbfb8aa3b, v80
	v_mul_f32_e32 v83, 0xbfb8aa3b, v83
	v_exp_f32_e32 v84, v84
	v_exp_f32_e32 v86, v86
	v_exp_f32_e32 v81, v81
	v_mul_f32_e32 v82, 0xbfb8aa3b, v82
	v_exp_f32_e32 v80, v80
	v_exp_f32_e32 v83, v83
	v_exp_f32_e32 v82, v82
	v_add_f32_e32 v85, 1.0, v85
	v_add_f32_e32 v87, 1.0, v87
	v_add_f32_e32 v84, 1.0, v84
	v_add_f32_e32 v86, 1.0, v86
	v_add_f32_e32 v81, 1.0, v81
	v_rcp_f32_e32 v85, v85
	v_rcp_f32_e32 v87, v87
	v_add_f32_e32 v80, 1.0, v80
	v_add_f32_e32 v83, 1.0, v83
	v_rcp_f32_e32 v84, v84
	v_rcp_f32_e32 v86, v86
	v_rcp_f32_e32 v81, v81
	v_add_f32_e32 v82, 1.0, v82
	v_rcp_f32_e32 v80, v80
	v_rcp_f32_e32 v83, v83
	v_rcp_f32_e32 v82, v82
	s_waitcnt vmcnt(1)
	v_and_b32_e32 v103, 0xffff0000, v170
	v_and_b32_e32 v119, 0xffff0000, v171
	v_lshlrev_b32_e32 v102, 16, v170
	v_lshlrev_b32_e32 v118, 16, v171
	v_and_b32_e32 v127, 0xffff0000, v172
	v_mul_f32_e32 v85, v85, v103
	v_mul_f32_e32 v87, v87, v119
	v_lshlrev_b32_e32 v126, 16, v172
	v_and_b32_e32 v163, 0xffff0000, v173
	v_mul_f32_e32 v84, v84, v102
	v_mul_f32_e32 v86, v86, v118
	v_mul_f32_e32 v81, v81, v127
	v_cvt_pk_bf16_f32 v170, v84, v85
	v_mul_f32_e32 v85, v85, v85
	v_mul_f32_e32 v102, v87, v87
	v_lshlrev_b32_e32 v147, 16, v173
	v_mul_f32_e32 v80, v80, v126
	v_mul_f32_e32 v83, v83, v163
	v_mul_f32_e32 v103, v81, v81
	v_fmac_f32_e32 v85, v84, v84
	v_fmac_f32_e32 v102, v86, v86
	v_mul_f32_e32 v82, v82, v147
	v_mul_f32_e32 v118, v83, v83
	v_fmac_f32_e32 v103, v80, v80
	v_add_f32_e32 v84, v85, v102
	v_add_f32_e32 v84, v103, v84
	v_fmac_f32_e32 v118, v82, v82
	v_add_f32_e32 v84, v118, v84
	v_mov_b32_e32 v244, v84
	v_mov_b32_e32 v85, v84
	s_nop 1
	v_permlane16_swap_b32_e32 v244, v85
	v_cvt_pk_bf16_f32 v171, v86, v87
	v_cvt_pk_bf16_f32 v172, v80, v81
	v_lshlrev_b64 v[80:81], 12, v[94:95]
	v_lshl_add_u64 v[80:81], s[58:59], 0, v[80:81]
	s_waitcnt lgkmcnt(0)
	v_add_f32_e32 v84, v84, v85
	v_mov_b32_e32 v244, v84
	v_mov_b32_e32 v85, v84
	s_nop 1
	v_permlane32_swap_b32_e32 v244, v85
	v_cvt_pk_bf16_f32 v173, v82, v83
	v_lshl_add_u64 v[82:83], v[80:81], 0, v[144:145]
	v_lshl_add_u64 v[80:81], v[94:95], 2, s[64:65]
	global_store_dwordx4 v[82:83], v[170:173], off offset:2048
	s_waitcnt lgkmcnt(0)
	v_add_f32_e32 v176, v84, v85
	v_mov_b32_e32 v178, v80
	v_mov_b32_e32 v179, v81
	v_add_u32_e32 v86, 0xa0, v146
	v_ashrrev_i32_e32 v87, 31, v86
	s_waitcnt lgkmcnt(0)
	v_lshlrev_b64 v[84:85], 11, v[86:87]
	v_lshl_add_u64 v[84:85], s[88:89], 0, v[84:85]
	v_lshl_add_u64 v[84:85], v[84:85], 0, v[144:145]
	global_load_dwordx4 v[170:173], v[84:85], off
	s_and_saveexec_b64 s[10:11], s[4:5]
	global_atomic_add_f32 v[178:179], v176, off
	s_mov_b64 exec, s[10:11]
	v_pk_add_f32 v[78:79], v[78:79], v[110:111]
	v_pk_add_f32 v[76:77], v[76:77], v[108:109]
	v_pk_add_f32 v[72:73], v[72:73], v[104:105]
	v_mul_f32_e32 v77, 0xbfb8aa3b, v77
	v_mul_f32_e32 v79, 0xbfb8aa3b, v79
	v_pk_add_f32 v[74:75], v[74:75], v[106:107]
	v_mul_f32_e32 v76, 0xbfb8aa3b, v76
	v_mul_f32_e32 v78, 0xbfb8aa3b, v78
	v_mul_f32_e32 v73, 0xbfb8aa3b, v73
	v_exp_f32_e32 v77, v77
	v_exp_f32_e32 v79, v79
	v_mul_f32_e32 v72, 0xbfb8aa3b, v72
	v_mul_f32_e32 v75, 0xbfb8aa3b, v75
	v_exp_f32_e32 v76, v76
	v_exp_f32_e32 v78, v78
	v_exp_f32_e32 v73, v73
	v_mul_f32_e32 v74, 0xbfb8aa3b, v74
	v_exp_f32_e32 v72, v72
	v_exp_f32_e32 v75, v75
	v_exp_f32_e32 v74, v74
	v_add_f32_e32 v77, 1.0, v77
	v_add_f32_e32 v79, 1.0, v79
	v_add_f32_e32 v76, 1.0, v76
	v_add_f32_e32 v78, 1.0, v78
	v_add_f32_e32 v73, 1.0, v73
	v_rcp_f32_e32 v77, v77
	v_rcp_f32_e32 v79, v79
	v_add_f32_e32 v72, 1.0, v72
	v_add_f32_e32 v75, 1.0, v75
	v_rcp_f32_e32 v76, v76
	v_rcp_f32_e32 v78, v78
	v_rcp_f32_e32 v73, v73
	v_add_f32_e32 v74, 1.0, v74
	v_rcp_f32_e32 v72, v72
	v_rcp_f32_e32 v75, v75
	v_rcp_f32_e32 v74, v74
	s_waitcnt vmcnt(1)
	v_and_b32_e32 v95, 0xffff0000, v170
	v_and_b32_e32 v103, 0xffff0000, v171
	v_lshlrev_b32_e32 v94, 16, v170
	v_lshlrev_b32_e32 v102, 16, v171
	v_and_b32_e32 v119, 0xffff0000, v172
	v_mul_f32_e32 v77, v77, v95
	v_mul_f32_e32 v79, v79, v103
	v_lshlrev_b32_e32 v118, 16, v172
	v_and_b32_e32 v127, 0xffff0000, v173
	v_mul_f32_e32 v76, v76, v94
	v_mul_f32_e32 v78, v78, v102
	v_mul_f32_e32 v73, v73, v119
	v_cvt_pk_bf16_f32 v170, v76, v77
	v_mul_f32_e32 v77, v77, v77
	v_mul_f32_e32 v94, v79, v79
	v_lshlrev_b32_e32 v126, 16, v173
	v_mul_f32_e32 v72, v72, v118
	v_mul_f32_e32 v75, v75, v127
	v_mul_f32_e32 v95, v73, v73
	v_fmac_f32_e32 v77, v76, v76
	v_fmac_f32_e32 v94, v78, v78
	v_mul_f32_e32 v74, v74, v126
	v_mul_f32_e32 v102, v75, v75
	v_fmac_f32_e32 v95, v72, v72
	v_add_f32_e32 v76, v77, v94
	v_add_f32_e32 v76, v95, v76
	v_fmac_f32_e32 v102, v74, v74
	v_add_f32_e32 v76, v102, v76
	v_mov_b32_e32 v244, v76
	v_mov_b32_e32 v77, v76
	s_nop 1
	v_permlane16_swap_b32_e32 v244, v77
	v_cvt_pk_bf16_f32 v171, v78, v79
	v_cvt_pk_bf16_f32 v172, v72, v73
	v_lshlrev_b64 v[72:73], 12, v[86:87]
	v_lshl_add_u64 v[72:73], s[58:59], 0, v[72:73]
	s_waitcnt lgkmcnt(0)
; __device__ __forceinline__ u32x4 pack8(f32x4 v0, f32x4 v1) { u32x4 w; w.x = cvt_pk_bf16(v0[0], v0[1]); w.y = cvt_pk_bf16(v0[2], v0[3]); w.z = cvt_pk_bf16(v1[0], v1[1]); w.w = cvt_pk_bf16(v1[2], v1[3]); return w; }
; __device__ __forceinline__ float sigmoidf_(float x) { return __builtin_amdgcn_rcpf(1.f + __builtin_amdgcn_exp2f(-1.4426950408889634f * x)); }
;     __device__ __forceinline__ void operator()(EPI_ARGS) const {
;     ...
;         for (int bj = 0; bj < 2; ++bj) { const int col0 = EPI_COL(bj); const f32x4 b0 = *(const f32x4*)(bias + col0), b1 = *(const f32x4*)(bias + col0 + 4);
; #pragma unroll
;             for (int ai = 0; ai < 2; ++ai)
; #pragma unroll
;                 for (int m = 0; m < 4; ++m) { const int row = EPI_ROW(ai, m); const u32x4 yv = *(const u32x4*)(Y + (size_t)row * 1024 + col0);
;                     f32x4 v0 = acc[ai][bj][m][0] + b0, v1 = acc[ai][bj][m][1] + b1;
;                     v0[0] = __uint_as_float(yv.x << 16) * sigmoidf_(v0[0]); v0[1] = __uint_as_float(yv.x & 0xffff0000u) * sigmoidf_(v0[1]);
;                     v0[2] = __uint_as_float(yv.y << 16) * sigmoidf_(v0[2]); v0[3] = __uint_as_float(yv.y & 0xffff0000u) * sigmoidf_(v0[3]);
;                     v1[0] = __uint_as_float(yv.z << 16) * sigmoidf_(v1[0]); v1[1] = __uint_as_float(yv.z & 0xffff0000u) * sigmoidf_(v1[1]);
;                     v1[2] = __uint_as_float(yv.w << 16) * sigmoidf_(v1[2]); v1[3] = __uint_as_float(yv.w & 0xffff0000u) * sigmoidf_(v1[3]);
;                     *(u32x4*)(MIX + (size_t)row * 2048 + 1024 + col0) = pack8(v0, v1);
;                     float ss = (v0[0] * v0[0] + v0[1] * v0[1]) + (v0[2] * v0[2] + v0[3] * v0[3]) + (v1[0] * v1[0] + v1[1] * v1[1]) + (v1[2] * v1[2] + v1[3] * v1[3]);
;                     ss += __shfl_xor(ss, 16); ss += __shfl_xor(ss, 32);
;                     if (fq == 0) atomicAdd(rsq + row, ss); } }
	v_add_f32_e32 v76, v76, v77
	v_mov_b32_e32 v244, v76
	v_mov_b32_e32 v77, v76
	s_nop 1
	v_permlane32_swap_b32_e32 v244, v77
	v_cvt_pk_bf16_f32 v173, v74, v75
	v_lshl_add_u64 v[74:75], v[72:73], 0, v[144:145]
	v_lshl_add_u64 v[72:73], v[86:87], 2, s[64:65]
	global_store_dwordx4 v[74:75], v[170:173], off offset:2048
	s_waitcnt lgkmcnt(0)
	v_add_f32_e32 v176, v76, v77
	v_mov_b32_e32 v178, v72
	v_mov_b32_e32 v179, v73
	v_add_u32_e32 v76, 0xb0, v146
	s_waitcnt lgkmcnt(0)
	v_ashrrev_i32_e32 v77, 31, v76
	v_lshlrev_b64 v[78:79], 11, v[76:77]
	v_lshl_add_u64 v[78:79], s[88:89], 0, v[78:79]
	v_lshl_add_u64 v[78:79], v[78:79], 0, v[144:145]
	global_load_dwordx4 v[170:173], v[78:79], off
	s_and_saveexec_b64 s[10:11], s[4:5]
	global_atomic_add_f32 v[178:179], v176, off
	s_mov_b64 exec, s[10:11]
	v_pk_add_f32 v[70:71], v[70:71], v[110:111]
	v_pk_add_f32 v[68:69], v[68:69], v[108:109]
	v_pk_add_f32 v[66:67], v[66:67], v[106:107]
	v_pk_add_f32 v[64:65], v[64:65], v[104:105]
	v_mul_f32_e32 v69, 0xbfb8aa3b, v69
	v_mul_f32_e32 v71, 0xbfb8aa3b, v71
	v_mul_f32_e32 v68, 0xbfb8aa3b, v68
	v_mul_f32_e32 v70, 0xbfb8aa3b, v70
	v_mul_f32_e32 v65, 0xbfb8aa3b, v65
	v_mul_f32_e32 v66, 0xbfb8aa3b, v66
	v_mul_f32_e32 v67, 0xbfb8aa3b, v67
	v_exp_f32_e32 v69, v69
	v_exp_f32_e32 v71, v71
	v_mul_f32_e32 v64, 0xbfb8aa3b, v64
	v_exp_f32_e32 v68, v68
	v_exp_f32_e32 v70, v70
	v_exp_f32_e32 v65, v65
	v_exp_f32_e32 v66, v66
	v_exp_f32_e32 v67, v67
	v_exp_f32_e32 v64, v64
	v_add_f32_e32 v69, 1.0, v69
	v_add_f32_e32 v71, 1.0, v71
	v_add_f32_e32 v68, 1.0, v68
	v_add_f32_e32 v70, 1.0, v70
	v_add_f32_e32 v65, 1.0, v65
	v_add_f32_e32 v66, 1.0, v66
	v_add_f32_e32 v67, 1.0, v67
	v_rcp_f32_e32 v69, v69
	v_rcp_f32_e32 v71, v71
	v_add_f32_e32 v64, 1.0, v64
	v_rcp_f32_e32 v68, v68
	v_rcp_f32_e32 v70, v70
	v_rcp_f32_e32 v65, v65
	v_rcp_f32_e32 v66, v66
	v_rcp_f32_e32 v67, v67
	v_rcp_f32_e32 v64, v64
	s_waitcnt vmcnt(1)
	v_and_b32_e32 v87, 0xffff0000, v170
	v_and_b32_e32 v95, 0xffff0000, v171
	v_lshlrev_b32_e32 v86, 16, v170
	v_lshlrev_b32_e32 v94, 16, v171
	v_and_b32_e32 v103, 0xffff0000, v172
	v_lshlrev_b32_e32 v104, 16, v173
	v_and_b32_e32 v105, 0xffff0000, v173
	v_mul_f32_e32 v69, v69, v87
	v_mul_f32_e32 v71, v71, v95
	v_lshlrev_b32_e32 v102, 16, v172
	v_mul_f32_e32 v68, v68, v86
	v_mul_f32_e32 v70, v70, v94
	v_mul_f32_e32 v65, v65, v103
	v_mul_f32_e32 v86, v66, v104
	v_mul_f32_e32 v87, v67, v105
	v_cvt_pk_bf16_f32 v66, v68, v69
	v_mul_f32_e32 v67, v69, v69
	v_mul_f32_e32 v69, v71, v71
	v_mul_f32_e32 v64, v64, v102
	v_mul_f32_e32 v94, v65, v65
	v_fmac_f32_e32 v67, v68, v68
	v_fmac_f32_e32 v69, v70, v70
	v_mul_f32_e32 v95, v87, v87
	v_fmac_f32_e32 v94, v64, v64
	v_add_f32_e32 v67, v67, v69
	v_add_f32_e32 v67, v94, v67
	v_fmac_f32_e32 v95, v86, v86
	v_add_f32_e32 v94, v95, v67
	v_mov_b32_e32 v244, v94
	v_mov_b32_e32 v95, v94
	s_nop 1
	v_permlane16_swap_b32_e32 v244, v95
	v_cvt_pk_bf16_f32 v67, v70, v71
	v_cvt_pk_bf16_f32 v68, v64, v65
	v_lshlrev_b64 v[70:71], 12, v[76:77]
	v_lshl_add_u64 v[70:71], s[58:59], 0, v[70:71]
	s_waitcnt lgkmcnt(0)
	v_add_f32_e32 v64, v94, v95
	v_mov_b32_e32 v244, v64
	v_mov_b32_e32 v65, v64
	s_nop 1
	v_permlane32_swap_b32_e32 v244, v65
	v_cvt_pk_bf16_f32 v69, v86, v87
	v_lshl_add_u64 v[86:87], v[70:71], 0, v[144:145]
	v_lshl_add_u64 v[76:77], v[76:77], 2, s[64:65]
	global_store_dwordx4 v[86:87], v[66:69], off offset:2048
	s_and_saveexec_b64 s[10:11], s[4:5]
	s_cbranch_execz .LBB0_615
	s_waitcnt lgkmcnt(0)
	v_add_f32_e32 v64, v64, v65
	global_atomic_add_f32 v[76:77], v64, off
.LBB0_615:
	s_or_b64 exec, exec, s[10:11]
	global_load_dwordx4 v[68:71], v[140:141], off offset:512
	s_waitcnt lgkmcnt(0)
	global_load_dwordx4 v[64:67], v[140:141], off offset:528
	global_load_dwordx4 v[102:105], v[142:143], off offset:256
	s_waitcnt vmcnt(2)
	v_pk_add_f32 v[62:63], v[62:63], v[70:71]
	v_pk_add_f32 v[60:61], v[60:61], v[68:69]
	s_waitcnt vmcnt(1)
	v_pk_add_f32 v[56:57], v[56:57], v[64:65]
	v_mul_f32_e32 v61, 0xbfb8aa3b, v61
	v_mul_f32_e32 v63, 0xbfb8aa3b, v63
	v_pk_add_f32 v[58:59], v[58:59], v[66:67]
	v_mul_f32_e32 v60, 0xbfb8aa3b, v60
	v_mul_f32_e32 v62, 0xbfb8aa3b, v62
	v_mul_f32_e32 v56, 0xbfb8aa3b, v56
	v_mul_f32_e32 v57, 0xbfb8aa3b, v57
	v_exp_f32_e32 v61, v61
	v_exp_f32_e32 v63, v63
	v_mul_f32_e32 v58, 0xbfb8aa3b, v58
	v_mul_f32_e32 v59, 0xbfb8aa3b, v59
	v_exp_f32_e32 v60, v60
	v_exp_f32_e32 v62, v62
	v_exp_f32_e32 v56, v56
	v_exp_f32_e32 v57, v57
	v_exp_f32_e32 v58, v58
	v_exp_f32_e32 v59, v59
	v_add_f32_e32 v61, 1.0, v61
	v_add_f32_e32 v63, 1.0, v63
	v_add_f32_e32 v60, 1.0, v60
	v_add_f32_e32 v62, 1.0, v62
	v_add_f32_e32 v56, 1.0, v56
	v_add_f32_e32 v57, 1.0, v57
	v_rcp_f32_e32 v61, v61
	v_rcp_f32_e32 v63, v63
	v_add_f32_e32 v58, 1.0, v58
	v_add_f32_e32 v59, 1.0, v59
	v_rcp_f32_e32 v60, v60
	v_rcp_f32_e32 v62, v62
	v_rcp_f32_e32 v56, v56
	v_rcp_f32_e32 v57, v57
	v_rcp_f32_e32 v58, v58
	v_rcp_f32_e32 v59, v59
	s_waitcnt vmcnt(0)
	v_lshlrev_b32_e32 v94, 16, v102
	v_and_b32_e32 v95, 0xffff0000, v102
	v_lshlrev_b32_e32 v102, 16, v103
	v_and_b32_e32 v103, 0xffff0000, v103
	v_lshlrev_b32_e32 v106, 16, v104
	v_and_b32_e32 v104, 0xffff0000, v104
	v_mul_f32_e32 v61, v61, v95
	v_mul_f32_e32 v63, v63, v103
	v_lshlrev_b32_e32 v107, 16, v105
	v_and_b32_e32 v105, 0xffff0000, v105
	v_mul_f32_e32 v60, v60, v94
	v_mul_f32_e32 v62, v62, v102
	v_mul_f32_e32 v94, v56, v106
	v_mul_f32_e32 v95, v57, v104
	v_mul_f32_e32 v56, v61, v61
	v_mul_f32_e32 v57, v63, v63
	v_mul_f32_e32 v102, v58, v107
	v_mul_f32_e32 v103, v59, v105
	v_mul_f32_e32 v58, v95, v95
	v_fmac_f32_e32 v56, v60, v60
	v_fmac_f32_e32 v57, v62, v62
	v_mul_f32_e32 v59, v103, v103
	v_fmac_f32_e32 v58, v94, v94
	v_add_f32_e32 v56, v56, v57
	v_add_f32_e32 v56, v56, v58
	v_fmac_f32_e32 v59, v102, v102
	v_add_f32_e32 v56, v59, v56
	v_mov_b32_e32 v244, v56
	v_mov_b32_e32 v57, v56
	s_nop 1
	v_permlane16_swap_b32_e32 v244, v57
	v_cvt_pk_bf16_f32 v58, v60, v61
	v_cvt_pk_bf16_f32 v59, v62, v63
	v_cvt_pk_bf16_f32 v60, v94, v95
	v_cvt_pk_bf16_f32 v61, v102, v103
	s_waitcnt lgkmcnt(0)
; __device__ __forceinline__ u32x4 pack8(f32x4 v0, f32x4 v1) { u32x4 w; w.x = cvt_pk_bf16(v0[0], v0[1]); w.y = cvt_pk_bf16(v0[2], v0[3]); w.z = cvt_pk_bf16(v1[0], v1[1]); w.w = cvt_pk_bf16(v1[2], v1[3]); return w; }
; __device__ __forceinline__ float sigmoidf_(float x) { return __builtin_amdgcn_rcpf(1.f + __builtin_amdgcn_exp2f(-1.4426950408889634f * x)); }
;     __device__ __forceinline__ void operator()(EPI_ARGS) const {
;     ...
;         for (int bj = 0; bj < 2; ++bj) { const int col0 = EPI_COL(bj); const f32x4 b0 = *(const f32x4*)(bias + col0), b1 = *(const f32x4*)(bias + col0 + 4);
; #pragma unroll
;             for (int ai = 0; ai < 2; ++ai)
; #pragma unroll
;                 for (int m = 0; m < 4; ++m) { const int row = EPI_ROW(ai, m); const u32x4 yv = *(const u32x4*)(Y + (size_t)row * 1024 + col0);
;                     f32x4 v0 = acc[ai][bj][m][0] + b0, v1 = acc[ai][bj][m][1] + b1;
;                     v0[0] = __uint_as_float(yv.x << 16) * sigmoidf_(v0[0]); v0[1] = __uint_as_float(yv.x & 0xffff0000u) * sigmoidf_(v0[1]);
;                     v0[2] = __uint_as_float(yv.y << 16) * sigmoidf_(v0[2]); v0[3] = __uint_as_float(yv.y & 0xffff0000u) * sigmoidf_(v0[3]);
;                     v1[0] = __uint_as_float(yv.z << 16) * sigmoidf_(v1[0]); v1[1] = __uint_as_float(yv.z & 0xffff0000u) * sigmoidf_(v1[1]);
;                     v1[2] = __uint_as_float(yv.w << 16) * sigmoidf_(v1[2]); v1[3] = __uint_as_float(yv.w & 0xffff0000u) * sigmoidf_(v1[3]);
;                     *(u32x4*)(MIX + (size_t)row * 2048 + 1024 + col0) = pack8(v0, v1);
;                     float ss = (v0[0] * v0[0] + v0[1] * v0[1]) + (v0[2] * v0[2] + v0[3] * v0[3]) + (v1[0] * v1[0] + v1[1] * v1[1]) + (v1[2] * v1[2] + v1[3] * v1[3]);
;                     ss += __shfl_xor(ss, 16); ss += __shfl_xor(ss, 32);
;                     if (fq == 0) atomicAdd(rsq + row, ss); } }
	v_add_f32_e32 v56, v56, v57
	v_mov_b32_e32 v244, v56
	v_mov_b32_e32 v57, v56
	s_nop 1
	v_permlane32_swap_b32_e32 v244, v57
	global_store_dwordx4 v[128:129], v[58:61], off offset:2304
	s_waitcnt lgkmcnt(0)
	v_add_f32_e32 v176, v56, v57
	v_mov_b32_e32 v178, v130
	v_mov_b32_e32 v179, v131
	s_waitcnt lgkmcnt(0)
	global_load_dwordx4 v[56:59], v[132:133], off offset:256
	s_and_saveexec_b64 s[10:11], s[4:5]
	global_atomic_add_f32 v[178:179], v176, off
	s_mov_b64 exec, s[10:11]
	v_pk_add_f32 v[54:55], v[54:55], v[70:71]
	v_pk_add_f32 v[52:53], v[52:53], v[68:69]
	v_pk_add_f32 v[48:49], v[48:49], v[64:65]
	v_mul_f32_e32 v53, 0xbfb8aa3b, v53
	v_mul_f32_e32 v55, 0xbfb8aa3b, v55
	v_pk_add_f32 v[50:51], v[50:51], v[66:67]
	v_mul_f32_e32 v52, 0xbfb8aa3b, v52
	v_mul_f32_e32 v54, 0xbfb8aa3b, v54
	v_mul_f32_e32 v48, 0xbfb8aa3b, v48
	v_mul_f32_e32 v49, 0xbfb8aa3b, v49
	v_exp_f32_e32 v53, v53
	v_exp_f32_e32 v55, v55
	v_mul_f32_e32 v50, 0xbfb8aa3b, v50
	v_mul_f32_e32 v51, 0xbfb8aa3b, v51
	v_exp_f32_e32 v52, v52
	v_exp_f32_e32 v54, v54
	v_exp_f32_e32 v48, v48
	v_exp_f32_e32 v49, v49
	v_exp_f32_e32 v50, v50
	v_exp_f32_e32 v51, v51
	v_add_f32_e32 v53, 1.0, v53
	v_add_f32_e32 v55, 1.0, v55
	v_add_f32_e32 v52, 1.0, v52
	v_add_f32_e32 v54, 1.0, v54
	v_add_f32_e32 v48, 1.0, v48
	v_add_f32_e32 v49, 1.0, v49
	v_rcp_f32_e32 v53, v53
	v_rcp_f32_e32 v55, v55
	v_add_f32_e32 v50, 1.0, v50
	v_add_f32_e32 v51, 1.0, v51
	v_rcp_f32_e32 v52, v52
	v_rcp_f32_e32 v54, v54
	v_rcp_f32_e32 v48, v48
	v_rcp_f32_e32 v49, v49
	v_rcp_f32_e32 v50, v50
	v_rcp_f32_e32 v51, v51
	s_waitcnt vmcnt(1)
	v_lshlrev_b32_e32 v60, 16, v56
	v_and_b32_e32 v56, 0xffff0000, v56
	v_lshlrev_b32_e32 v61, 16, v57
	v_and_b32_e32 v57, 0xffff0000, v57
	v_lshlrev_b32_e32 v62, 16, v58
	v_and_b32_e32 v58, 0xffff0000, v58
	v_mul_f32_e32 v53, v53, v56
	v_mul_f32_e32 v55, v55, v57
	v_lshlrev_b32_e32 v63, 16, v59
	v_and_b32_e32 v59, 0xffff0000, v59
	v_mul_f32_e32 v52, v52, v60
	v_mul_f32_e32 v54, v54, v61
	v_mul_f32_e32 v56, v48, v62
	v_mul_f32_e32 v57, v49, v58
	v_mul_f32_e32 v48, v53, v53
	v_mul_f32_e32 v49, v55, v55
	v_mul_f32_e32 v58, v50, v63
	v_mul_f32_e32 v59, v51, v59
	v_mul_f32_e32 v50, v57, v57
	v_fmac_f32_e32 v48, v52, v52
	v_fmac_f32_e32 v49, v54, v54
	v_mul_f32_e32 v51, v59, v59
	v_fmac_f32_e32 v50, v56, v56
	v_add_f32_e32 v48, v48, v49
	v_add_f32_e32 v48, v50, v48
	v_fmac_f32_e32 v51, v58, v58
	v_add_f32_e32 v48, v51, v48
	v_mov_b32_e32 v244, v48
	v_mov_b32_e32 v49, v48
	s_nop 1
	v_permlane16_swap_b32_e32 v244, v49
	v_cvt_pk_bf16_f32 v50, v52, v53
	v_cvt_pk_bf16_f32 v51, v54, v55
	v_cvt_pk_bf16_f32 v52, v56, v57
	v_cvt_pk_bf16_f32 v53, v58, v59
	s_waitcnt lgkmcnt(0)
	v_add_f32_e32 v48, v48, v49
	v_mov_b32_e32 v244, v48
	v_mov_b32_e32 v49, v48
	s_nop 1
	v_permlane32_swap_b32_e32 v244, v49
	global_store_dwordx4 v[122:123], v[50:53], off offset:2304
	s_waitcnt lgkmcnt(0)
	v_add_f32_e32 v176, v48, v49
	v_mov_b32_e32 v178, v120
	v_mov_b32_e32 v179, v121
	s_waitcnt lgkmcnt(0)
	global_load_dwordx4 v[48:51], v[124:125], off offset:256
	s_and_saveexec_b64 s[10:11], s[4:5]
	global_atomic_add_f32 v[178:179], v176, off
	s_mov_b64 exec, s[10:11]
	v_pk_add_f32 v[46:47], v[46:47], v[70:71]
	v_pk_add_f32 v[44:45], v[44:45], v[68:69]
	v_pk_add_f32 v[40:41], v[40:41], v[64:65]
	v_mul_f32_e32 v45, 0xbfb8aa3b, v45
	v_mul_f32_e32 v47, 0xbfb8aa3b, v47
	v_pk_add_f32 v[42:43], v[42:43], v[66:67]
	v_mul_f32_e32 v44, 0xbfb8aa3b, v44
	v_mul_f32_e32 v46, 0xbfb8aa3b, v46
	v_mul_f32_e32 v40, 0xbfb8aa3b, v40
	v_mul_f32_e32 v41, 0xbfb8aa3b, v41
	v_exp_f32_e32 v45, v45
	v_exp_f32_e32 v47, v47
	v_mul_f32_e32 v42, 0xbfb8aa3b, v42
	v_mul_f32_e32 v43, 0xbfb8aa3b, v43
	v_exp_f32_e32 v44, v44
	v_exp_f32_e32 v46, v46
	v_exp_f32_e32 v40, v40
	v_exp_f32_e32 v41, v41
	v_exp_f32_e32 v42, v42
	v_exp_f32_e32 v43, v43
	v_add_f32_e32 v45, 1.0, v45
	v_add_f32_e32 v47, 1.0, v47
	v_add_f32_e32 v44, 1.0, v44
	v_add_f32_e32 v46, 1.0, v46
	v_add_f32_e32 v40, 1.0, v40
	v_add_f32_e32 v41, 1.0, v41
	v_rcp_f32_e32 v45, v45
	v_rcp_f32_e32 v47, v47
	v_add_f32_e32 v42, 1.0, v42
	v_add_f32_e32 v43, 1.0, v43
	v_rcp_f32_e32 v44, v44
	v_rcp_f32_e32 v46, v46
	v_rcp_f32_e32 v40, v40
	v_rcp_f32_e32 v41, v41
	v_rcp_f32_e32 v42, v42
	v_rcp_f32_e32 v43, v43
	s_waitcnt vmcnt(1)
	v_lshlrev_b32_e32 v52, 16, v48
	v_and_b32_e32 v48, 0xffff0000, v48
	v_lshlrev_b32_e32 v53, 16, v49
	v_and_b32_e32 v49, 0xffff0000, v49
	v_lshlrev_b32_e32 v54, 16, v50
	v_and_b32_e32 v50, 0xffff0000, v50
	v_mul_f32_e32 v45, v45, v48
	v_mul_f32_e32 v47, v47, v49
	v_lshlrev_b32_e32 v55, 16, v51
	v_and_b32_e32 v51, 0xffff0000, v51
	v_mul_f32_e32 v44, v44, v52
	v_mul_f32_e32 v46, v46, v53
	v_mul_f32_e32 v48, v40, v54
	v_mul_f32_e32 v49, v41, v50
	v_mul_f32_e32 v40, v45, v45
	v_mul_f32_e32 v41, v47, v47
	v_mul_f32_e32 v50, v42, v55
	v_mul_f32_e32 v51, v43, v51
	v_mul_f32_e32 v42, v49, v49
	v_fmac_f32_e32 v40, v44, v44
	v_fmac_f32_e32 v41, v46, v46
	v_mul_f32_e32 v43, v51, v51
	v_fmac_f32_e32 v42, v48, v48
	v_add_f32_e32 v40, v40, v41
	v_add_f32_e32 v40, v42, v40
	v_fmac_f32_e32 v43, v50, v50
	v_add_f32_e32 v40, v43, v40
	v_mov_b32_e32 v244, v40
	v_mov_b32_e32 v41, v40
	s_nop 1
	v_permlane16_swap_b32_e32 v244, v41
	v_cvt_pk_bf16_f32 v42, v44, v45
	v_cvt_pk_bf16_f32 v43, v46, v47
	v_cvt_pk_bf16_f32 v44, v48, v49
	v_cvt_pk_bf16_f32 v45, v50, v51
	s_waitcnt lgkmcnt(0)
	v_add_f32_e32 v40, v40, v41
	v_mov_b32_e32 v244, v40
	v_mov_b32_e32 v41, v40
	s_nop 1
	v_permlane32_swap_b32_e32 v244, v41
	global_store_dwordx4 v[114:115], v[42:45], off offset:2304
	s_waitcnt lgkmcnt(0)
	v_add_f32_e32 v176, v40, v41
	v_mov_b32_e32 v178, v112
	v_mov_b32_e32 v179, v113
	s_waitcnt lgkmcnt(0)
; __device__ __forceinline__ u32x4 pack8(f32x4 v0, f32x4 v1) { u32x4 w; w.x = cvt_pk_bf16(v0[0], v0[1]); w.y = cvt_pk_bf16(v0[2], v0[3]); w.z = cvt_pk_bf16(v1[0], v1[1]); w.w = cvt_pk_bf16(v1[2], v1[3]); return w; }
; __device__ __forceinline__ float sigmoidf_(float x) { return __builtin_amdgcn_rcpf(1.f + __builtin_amdgcn_exp2f(-1.4426950408889634f * x)); }
;     __device__ __forceinline__ void operator()(EPI_ARGS) const {
;     ...
;         for (int bj = 0; bj < 2; ++bj) { const int col0 = EPI_COL(bj); const f32x4 b0 = *(const f32x4*)(bias + col0), b1 = *(const f32x4*)(bias + col0 + 4);
; #pragma unroll
;             for (int ai = 0; ai < 2; ++ai)
; #pragma unroll
;                 for (int m = 0; m < 4; ++m) { const int row = EPI_ROW(ai, m); const u32x4 yv = *(const u32x4*)(Y + (size_t)row * 1024 + col0);
;                     f32x4 v0 = acc[ai][bj][m][0] + b0, v1 = acc[ai][bj][m][1] + b1;
;                     v0[0] = __uint_as_float(yv.x << 16) * sigmoidf_(v0[0]); v0[1] = __uint_as_float(yv.x & 0xffff0000u) * sigmoidf_(v0[1]);
;                     v0[2] = __uint_as_float(yv.y << 16) * sigmoidf_(v0[2]); v0[3] = __uint_as_float(yv.y & 0xffff0000u) * sigmoidf_(v0[3]);
;                     v1[0] = __uint_as_float(yv.z << 16) * sigmoidf_(v1[0]); v1[1] = __uint_as_float(yv.z & 0xffff0000u) * sigmoidf_(v1[1]);
;                     v1[2] = __uint_as_float(yv.w << 16) * sigmoidf_(v1[2]); v1[3] = __uint_as_float(yv.w & 0xffff0000u) * sigmoidf_(v1[3]);
;                     *(u32x4*)(MIX + (size_t)row * 2048 + 1024 + col0) = pack8(v0, v1);
;                     float ss = (v0[0] * v0[0] + v0[1] * v0[1]) + (v0[2] * v0[2] + v0[3] * v0[3]) + (v1[0] * v1[0] + v1[1] * v1[1]) + (v1[2] * v1[2] + v1[3] * v1[3]);
;                     ss += __shfl_xor(ss, 16); ss += __shfl_xor(ss, 32);
;                     if (fq == 0) atomicAdd(rsq + row, ss); } }
	global_load_dwordx4 v[40:43], v[116:117], off offset:256
	s_and_saveexec_b64 s[10:11], s[4:5]
	global_atomic_add_f32 v[178:179], v176, off
	s_mov_b64 exec, s[10:11]
	v_pk_add_f32 v[38:39], v[38:39], v[70:71]
	v_pk_add_f32 v[36:37], v[36:37], v[68:69]
	v_pk_add_f32 v[32:33], v[32:33], v[64:65]
	v_mul_f32_e32 v37, 0xbfb8aa3b, v37
	v_mul_f32_e32 v39, 0xbfb8aa3b, v39
	v_pk_add_f32 v[34:35], v[34:35], v[66:67]
	v_mul_f32_e32 v36, 0xbfb8aa3b, v36
	v_mul_f32_e32 v38, 0xbfb8aa3b, v38
	v_mul_f32_e32 v32, 0xbfb8aa3b, v32
	v_mul_f32_e32 v33, 0xbfb8aa3b, v33
	v_exp_f32_e32 v37, v37
	v_exp_f32_e32 v39, v39
	v_mul_f32_e32 v34, 0xbfb8aa3b, v34
	v_mul_f32_e32 v35, 0xbfb8aa3b, v35
	v_exp_f32_e32 v36, v36
	v_exp_f32_e32 v38, v38
	v_exp_f32_e32 v32, v32
	v_exp_f32_e32 v33, v33
	v_exp_f32_e32 v34, v34
	v_exp_f32_e32 v35, v35
	v_add_f32_e32 v37, 1.0, v37
	v_add_f32_e32 v39, 1.0, v39
	v_add_f32_e32 v36, 1.0, v36
	v_add_f32_e32 v38, 1.0, v38
	v_add_f32_e32 v32, 1.0, v32
	v_add_f32_e32 v33, 1.0, v33
	v_rcp_f32_e32 v37, v37
	v_rcp_f32_e32 v39, v39
	v_add_f32_e32 v34, 1.0, v34
	v_add_f32_e32 v35, 1.0, v35
	v_rcp_f32_e32 v36, v36
	v_rcp_f32_e32 v38, v38
	v_rcp_f32_e32 v32, v32
	v_rcp_f32_e32 v33, v33
	v_rcp_f32_e32 v34, v34
	v_rcp_f32_e32 v35, v35
	s_waitcnt vmcnt(1)
	v_lshlrev_b32_e32 v44, 16, v40
	v_and_b32_e32 v40, 0xffff0000, v40
	v_lshlrev_b32_e32 v45, 16, v41
	v_and_b32_e32 v41, 0xffff0000, v41
	v_lshlrev_b32_e32 v46, 16, v42
	v_and_b32_e32 v42, 0xffff0000, v42
	v_mul_f32_e32 v37, v37, v40
	v_mul_f32_e32 v39, v39, v41
	v_lshlrev_b32_e32 v47, 16, v43
	v_and_b32_e32 v43, 0xffff0000, v43
	v_mul_f32_e32 v36, v36, v44
	v_mul_f32_e32 v38, v38, v45
	v_mul_f32_e32 v40, v32, v46
	v_mul_f32_e32 v41, v33, v42
	v_mul_f32_e32 v32, v37, v37
	v_mul_f32_e32 v33, v39, v39
	v_mul_f32_e32 v42, v34, v47
	v_mul_f32_e32 v43, v35, v43
	v_mul_f32_e32 v34, v41, v41
	v_fmac_f32_e32 v32, v36, v36
	v_fmac_f32_e32 v33, v38, v38
	v_mul_f32_e32 v35, v43, v43
	v_fmac_f32_e32 v34, v40, v40
	v_add_f32_e32 v32, v32, v33
	v_add_f32_e32 v32, v34, v32
	v_fmac_f32_e32 v35, v42, v42
	v_add_f32_e32 v32, v35, v32
	v_mov_b32_e32 v244, v32
	v_mov_b32_e32 v33, v32
	s_nop 1
	v_permlane16_swap_b32_e32 v244, v33
	v_cvt_pk_bf16_f32 v34, v36, v37
	v_cvt_pk_bf16_f32 v35, v38, v39
	v_cvt_pk_bf16_f32 v36, v40, v41
	v_cvt_pk_bf16_f32 v37, v42, v43
	s_waitcnt lgkmcnt(0)
	v_add_f32_e32 v32, v32, v33
	v_mov_b32_e32 v244, v32
	v_mov_b32_e32 v33, v32
	s_nop 1
	v_permlane32_swap_b32_e32 v244, v33
	global_store_dwordx4 v[98:99], v[34:37], off offset:2304
	s_waitcnt lgkmcnt(0)
	v_add_f32_e32 v176, v32, v33
	v_mov_b32_e32 v178, v96
	v_mov_b32_e32 v179, v97
	s_waitcnt lgkmcnt(0)
	global_load_dwordx4 v[32:35], v[100:101], off offset:256
	s_and_saveexec_b64 s[10:11], s[4:5]
	global_atomic_add_f32 v[178:179], v176, off
	s_mov_b64 exec, s[10:11]
	v_pk_add_f32 v[30:31], v[30:31], v[70:71]
	v_pk_add_f32 v[28:29], v[28:29], v[68:69]
	v_pk_add_f32 v[24:25], v[24:25], v[64:65]
	v_mul_f32_e32 v29, 0xbfb8aa3b, v29
	v_mul_f32_e32 v31, 0xbfb8aa3b, v31
	v_pk_add_f32 v[26:27], v[26:27], v[66:67]
	v_mul_f32_e32 v28, 0xbfb8aa3b, v28
	v_mul_f32_e32 v30, 0xbfb8aa3b, v30
	v_mul_f32_e32 v24, 0xbfb8aa3b, v24
	v_mul_f32_e32 v25, 0xbfb8aa3b, v25
	v_exp_f32_e32 v29, v29
	v_exp_f32_e32 v31, v31
	v_mul_f32_e32 v26, 0xbfb8aa3b, v26
	v_mul_f32_e32 v27, 0xbfb8aa3b, v27
	v_exp_f32_e32 v28, v28
	v_exp_f32_e32 v30, v30
	v_exp_f32_e32 v24, v24
	v_exp_f32_e32 v25, v25
	v_exp_f32_e32 v26, v26
	v_exp_f32_e32 v27, v27
	v_add_f32_e32 v29, 1.0, v29
	v_add_f32_e32 v31, 1.0, v31
	v_add_f32_e32 v28, 1.0, v28
	v_add_f32_e32 v30, 1.0, v30
	v_add_f32_e32 v24, 1.0, v24
	v_add_f32_e32 v25, 1.0, v25
	v_rcp_f32_e32 v29, v29
	v_rcp_f32_e32 v31, v31
	v_add_f32_e32 v26, 1.0, v26
	v_add_f32_e32 v27, 1.0, v27
	v_rcp_f32_e32 v28, v28
	v_rcp_f32_e32 v30, v30
	v_rcp_f32_e32 v24, v24
	v_rcp_f32_e32 v25, v25
	v_rcp_f32_e32 v26, v26
	v_rcp_f32_e32 v27, v27
	s_waitcnt vmcnt(1)
	v_lshlrev_b32_e32 v36, 16, v32
	v_and_b32_e32 v32, 0xffff0000, v32
	v_lshlrev_b32_e32 v37, 16, v33
	v_and_b32_e32 v33, 0xffff0000, v33
	v_lshlrev_b32_e32 v38, 16, v34
	v_and_b32_e32 v34, 0xffff0000, v34
	v_mul_f32_e32 v29, v29, v32
	v_mul_f32_e32 v31, v31, v33
	v_lshlrev_b32_e32 v39, 16, v35
	v_and_b32_e32 v35, 0xffff0000, v35
	v_mul_f32_e32 v28, v28, v36
	v_mul_f32_e32 v30, v30, v37
	v_mul_f32_e32 v32, v24, v38
	v_mul_f32_e32 v33, v25, v34
	v_mul_f32_e32 v24, v29, v29
	v_mul_f32_e32 v25, v31, v31
	v_mul_f32_e32 v34, v26, v39
	v_mul_f32_e32 v35, v27, v35
	v_mul_f32_e32 v26, v33, v33
	v_fmac_f32_e32 v24, v28, v28
	v_fmac_f32_e32 v25, v30, v30
	v_mul_f32_e32 v27, v35, v35
	v_fmac_f32_e32 v26, v32, v32
	v_add_f32_e32 v24, v24, v25
	v_add_f32_e32 v24, v26, v24
	v_fmac_f32_e32 v27, v34, v34
	v_add_f32_e32 v24, v27, v24
	v_mov_b32_e32 v244, v24
	v_mov_b32_e32 v25, v24
	s_nop 1
	v_permlane16_swap_b32_e32 v244, v25
	v_cvt_pk_bf16_f32 v26, v28, v29
	v_cvt_pk_bf16_f32 v27, v30, v31
	v_cvt_pk_bf16_f32 v28, v32, v33
	v_cvt_pk_bf16_f32 v29, v34, v35
	s_waitcnt lgkmcnt(0)
	v_add_f32_e32 v24, v24, v25
	v_mov_b32_e32 v244, v24
	v_mov_b32_e32 v25, v24
	s_nop 1
	v_permlane32_swap_b32_e32 v244, v25
	global_store_dwordx4 v[90:91], v[26:29], off offset:2304
	s_waitcnt lgkmcnt(0)
	v_add_f32_e32 v176, v24, v25
	v_mov_b32_e32 v178, v88
	v_mov_b32_e32 v179, v89
	s_waitcnt lgkmcnt(0)
; __device__ __forceinline__ u32x4 pack8(f32x4 v0, f32x4 v1) { u32x4 w; w.x = cvt_pk_bf16(v0[0], v0[1]); w.y = cvt_pk_bf16(v0[2], v0[3]); w.z = cvt_pk_bf16(v1[0], v1[1]); w.w = cvt_pk_bf16(v1[2], v1[3]); return w; }
; __device__ __forceinline__ float sigmoidf_(float x) { return __builtin_amdgcn_rcpf(1.f + __builtin_amdgcn_exp2f(-1.4426950408889634f * x)); }
;     __device__ __forceinline__ void operator()(EPI_ARGS) const {
;     ...
;         for (int bj = 0; bj < 2; ++bj) { const int col0 = EPI_COL(bj); const f32x4 b0 = *(const f32x4*)(bias + col0), b1 = *(const f32x4*)(bias + col0 + 4);
; #pragma unroll
;             for (int ai = 0; ai < 2; ++ai)
; #pragma unroll
;                 for (int m = 0; m < 4; ++m) { const int row = EPI_ROW(ai, m); const u32x4 yv = *(const u32x4*)(Y + (size_t)row * 1024 + col0);
;                     f32x4 v0 = acc[ai][bj][m][0] + b0, v1 = acc[ai][bj][m][1] + b1;
;                     v0[0] = __uint_as_float(yv.x << 16) * sigmoidf_(v0[0]); v0[1] = __uint_as_float(yv.x & 0xffff0000u) * sigmoidf_(v0[1]);
;                     v0[2] = __uint_as_float(yv.y << 16) * sigmoidf_(v0[2]); v0[3] = __uint_as_float(yv.y & 0xffff0000u) * sigmoidf_(v0[3]);
;                     v1[0] = __uint_as_float(yv.z << 16) * sigmoidf_(v1[0]); v1[1] = __uint_as_float(yv.z & 0xffff0000u) * sigmoidf_(v1[1]);
;                     v1[2] = __uint_as_float(yv.w << 16) * sigmoidf_(v1[2]); v1[3] = __uint_as_float(yv.w & 0xffff0000u) * sigmoidf_(v1[3]);
;                     *(u32x4*)(MIX + (size_t)row * 2048 + 1024 + col0) = pack8(v0, v1);
;                     float ss = (v0[0] * v0[0] + v0[1] * v0[1]) + (v0[2] * v0[2] + v0[3] * v0[3]) + (v1[0] * v1[0] + v1[1] * v1[1]) + (v1[2] * v1[2] + v1[3] * v1[3]);
;                     ss += __shfl_xor(ss, 16); ss += __shfl_xor(ss, 32);
;                     if (fq == 0) atomicAdd(rsq + row, ss); } }
	global_load_dwordx4 v[24:27], v[92:93], off offset:256
	s_and_saveexec_b64 s[10:11], s[4:5]
	global_atomic_add_f32 v[178:179], v176, off
	s_mov_b64 exec, s[10:11]
	v_pk_add_f32 v[22:23], v[22:23], v[70:71]
	v_pk_add_f32 v[20:21], v[20:21], v[68:69]
	v_pk_add_f32 v[16:17], v[16:17], v[64:65]
	v_mul_f32_e32 v21, 0xbfb8aa3b, v21
	v_mul_f32_e32 v23, 0xbfb8aa3b, v23
	v_pk_add_f32 v[18:19], v[18:19], v[66:67]
	v_mul_f32_e32 v20, 0xbfb8aa3b, v20
	v_mul_f32_e32 v22, 0xbfb8aa3b, v22
	v_mul_f32_e32 v16, 0xbfb8aa3b, v16
	v_mul_f32_e32 v17, 0xbfb8aa3b, v17
	v_exp_f32_e32 v21, v21
	v_exp_f32_e32 v23, v23
	v_mul_f32_e32 v18, 0xbfb8aa3b, v18
	v_mul_f32_e32 v19, 0xbfb8aa3b, v19
	v_exp_f32_e32 v20, v20
	v_exp_f32_e32 v22, v22
	v_exp_f32_e32 v16, v16
	v_exp_f32_e32 v17, v17
	v_exp_f32_e32 v18, v18
	v_exp_f32_e32 v19, v19
	v_add_f32_e32 v21, 1.0, v21
	v_add_f32_e32 v23, 1.0, v23
	v_add_f32_e32 v20, 1.0, v20
	v_add_f32_e32 v22, 1.0, v22
	v_add_f32_e32 v16, 1.0, v16
	v_add_f32_e32 v17, 1.0, v17
	v_rcp_f32_e32 v21, v21
	v_rcp_f32_e32 v23, v23
	v_add_f32_e32 v18, 1.0, v18
	v_add_f32_e32 v19, 1.0, v19
	v_rcp_f32_e32 v20, v20
	v_rcp_f32_e32 v22, v22
	v_rcp_f32_e32 v16, v16
	v_rcp_f32_e32 v17, v17
	v_rcp_f32_e32 v18, v18
	v_rcp_f32_e32 v19, v19
	s_waitcnt vmcnt(1)
	v_lshlrev_b32_e32 v28, 16, v24
	v_and_b32_e32 v24, 0xffff0000, v24
	v_lshlrev_b32_e32 v29, 16, v25
	v_and_b32_e32 v25, 0xffff0000, v25
	v_lshlrev_b32_e32 v30, 16, v26
	v_and_b32_e32 v26, 0xffff0000, v26
	v_mul_f32_e32 v21, v21, v24
	v_mul_f32_e32 v23, v23, v25
	v_lshlrev_b32_e32 v31, 16, v27
	v_and_b32_e32 v27, 0xffff0000, v27
	v_mul_f32_e32 v20, v20, v28
	v_mul_f32_e32 v22, v22, v29
	v_mul_f32_e32 v24, v16, v30
	v_mul_f32_e32 v25, v17, v26
	v_mul_f32_e32 v16, v21, v21
	v_mul_f32_e32 v17, v23, v23
	v_mul_f32_e32 v26, v18, v31
	v_mul_f32_e32 v27, v19, v27
	v_mul_f32_e32 v18, v25, v25
	v_fmac_f32_e32 v16, v20, v20
	v_fmac_f32_e32 v17, v22, v22
	v_mul_f32_e32 v19, v27, v27
	v_fmac_f32_e32 v18, v24, v24
	v_add_f32_e32 v16, v16, v17
	v_add_f32_e32 v16, v18, v16
	v_fmac_f32_e32 v19, v26, v26
	v_add_f32_e32 v16, v19, v16
	v_mov_b32_e32 v244, v16
	v_mov_b32_e32 v17, v16
	s_nop 1
	v_permlane16_swap_b32_e32 v244, v17
	v_cvt_pk_bf16_f32 v18, v20, v21
	v_cvt_pk_bf16_f32 v19, v22, v23
	v_cvt_pk_bf16_f32 v20, v24, v25
	v_cvt_pk_bf16_f32 v21, v26, v27
	s_waitcnt lgkmcnt(0)
	v_add_f32_e32 v16, v16, v17
	v_mov_b32_e32 v244, v16
	v_mov_b32_e32 v17, v16
	s_nop 1
	v_permlane32_swap_b32_e32 v244, v17
	global_store_dwordx4 v[82:83], v[18:21], off offset:2304
	s_waitcnt lgkmcnt(0)
	v_add_f32_e32 v176, v16, v17
	v_mov_b32_e32 v178, v80
	v_mov_b32_e32 v179, v81
	s_waitcnt lgkmcnt(0)
	global_load_dwordx4 v[16:19], v[84:85], off offset:256
	s_and_saveexec_b64 s[10:11], s[4:5]
	global_atomic_add_f32 v[178:179], v176, off
	s_mov_b64 exec, s[10:11]
	v_pk_add_f32 v[14:15], v[14:15], v[70:71]
	v_pk_add_f32 v[12:13], v[12:13], v[68:69]
	v_pk_add_f32 v[8:9], v[8:9], v[64:65]
	v_mul_f32_e32 v13, 0xbfb8aa3b, v13
	v_mul_f32_e32 v15, 0xbfb8aa3b, v15
	v_pk_add_f32 v[10:11], v[10:11], v[66:67]
	v_mul_f32_e32 v12, 0xbfb8aa3b, v12
	v_mul_f32_e32 v14, 0xbfb8aa3b, v14
	v_mul_f32_e32 v8, 0xbfb8aa3b, v8
	v_mul_f32_e32 v9, 0xbfb8aa3b, v9
	v_exp_f32_e32 v13, v13
	v_exp_f32_e32 v15, v15
	v_mul_f32_e32 v10, 0xbfb8aa3b, v10
	v_mul_f32_e32 v11, 0xbfb8aa3b, v11
	v_exp_f32_e32 v12, v12
	v_exp_f32_e32 v14, v14
	v_exp_f32_e32 v8, v8
	v_exp_f32_e32 v9, v9
	v_exp_f32_e32 v10, v10
	v_exp_f32_e32 v11, v11
	v_add_f32_e32 v13, 1.0, v13
	v_add_f32_e32 v15, 1.0, v15
	v_add_f32_e32 v12, 1.0, v12
	v_add_f32_e32 v14, 1.0, v14
	v_add_f32_e32 v8, 1.0, v8
	v_add_f32_e32 v9, 1.0, v9
	v_rcp_f32_e32 v13, v13
	v_rcp_f32_e32 v15, v15
	v_add_f32_e32 v10, 1.0, v10
	v_add_f32_e32 v11, 1.0, v11
	v_rcp_f32_e32 v12, v12
	v_rcp_f32_e32 v14, v14
	v_rcp_f32_e32 v8, v8
	v_rcp_f32_e32 v9, v9
	v_rcp_f32_e32 v10, v10
	v_rcp_f32_e32 v11, v11
	s_waitcnt vmcnt(1)
; __device__ __forceinline__ u32x4 pack8(f32x4 v0, f32x4 v1) { u32x4 w; w.x = cvt_pk_bf16(v0[0], v0[1]); w.y = cvt_pk_bf16(v0[2], v0[3]); w.z = cvt_pk_bf16(v1[0], v1[1]); w.w = cvt_pk_bf16(v1[2], v1[3]); return w; }
; __device__ __forceinline__ float sigmoidf_(float x) { return __builtin_amdgcn_rcpf(1.f + __builtin_amdgcn_exp2f(-1.4426950408889634f * x)); }
;     __device__ __forceinline__ void operator()(EPI_ARGS) const {
;     ...
;                 for (int m = 0; m < 4; ++m) { const int row = EPI_ROW(ai, m); const u32x4 yv = *(const u32x4*)(Y + (size_t)row * 1024 + col0);
;                     f32x4 v0 = acc[ai][bj][m][0] + b0, v1 = acc[ai][bj][m][1] + b1;
;                     v0[0] = __uint_as_float(yv.x << 16) * sigmoidf_(v0[0]); v0[1] = __uint_as_float(yv.x & 0xffff0000u) * sigmoidf_(v0[1]);
;                     v0[2] = __uint_as_float(yv.y << 16) * sigmoidf_(v0[2]); v0[3] = __uint_as_float(yv.y & 0xffff0000u) * sigmoidf_(v0[3]);
;                     v1[0] = __uint_as_float(yv.z << 16) * sigmoidf_(v1[0]); v1[1] = __uint_as_float(yv.z & 0xffff0000u) * sigmoidf_(v1[1]);
;                     v1[2] = __uint_as_float(yv.w << 16) * sigmoidf_(v1[2]); v1[3] = __uint_as_float(yv.w & 0xffff0000u) * sigmoidf_(v1[3]);
;                     *(u32x4*)(MIX + (size_t)row * 2048 + 1024 + col0) = pack8(v0, v1);
;                     float ss = (v0[0] * v0[0] + v0[1] * v0[1]) + (v0[2] * v0[2] + v0[3] * v0[3]) + (v1[0] * v1[0] + v1[1] * v1[1]) + (v1[2] * v1[2] + v1[3] * v1[3]);
;                     ss += __shfl_xor(ss, 16); ss += __shfl_xor(ss, 32);
;                     if (fq == 0) atomicAdd(rsq + row, ss); } }
	v_lshlrev_b32_e32 v20, 16, v16
	v_and_b32_e32 v16, 0xffff0000, v16
	v_lshlrev_b32_e32 v21, 16, v17
	v_and_b32_e32 v17, 0xffff0000, v17
	v_lshlrev_b32_e32 v22, 16, v18
	v_and_b32_e32 v18, 0xffff0000, v18
	v_mul_f32_e32 v13, v13, v16
	v_mul_f32_e32 v15, v15, v17
	v_lshlrev_b32_e32 v23, 16, v19
	v_and_b32_e32 v19, 0xffff0000, v19
	v_mul_f32_e32 v12, v12, v20
	v_mul_f32_e32 v14, v14, v21
	v_mul_f32_e32 v16, v8, v22
	v_mul_f32_e32 v17, v9, v18
	v_mul_f32_e32 v8, v13, v13
	v_mul_f32_e32 v9, v15, v15
	v_mul_f32_e32 v18, v10, v23
	v_mul_f32_e32 v19, v11, v19
	v_mul_f32_e32 v10, v17, v17
	v_fmac_f32_e32 v8, v12, v12
	v_fmac_f32_e32 v9, v14, v14
	v_mul_f32_e32 v11, v19, v19
	v_fmac_f32_e32 v10, v16, v16
	v_add_f32_e32 v8, v8, v9
	v_add_f32_e32 v8, v10, v8
	v_fmac_f32_e32 v11, v18, v18
	v_add_f32_e32 v8, v11, v8
	v_mov_b32_e32 v244, v8
	v_mov_b32_e32 v9, v8
	s_nop 1
	v_permlane16_swap_b32_e32 v244, v9
	v_cvt_pk_bf16_f32 v10, v12, v13
	v_cvt_pk_bf16_f32 v11, v14, v15
	v_cvt_pk_bf16_f32 v12, v16, v17
	v_cvt_pk_bf16_f32 v13, v18, v19
	s_waitcnt lgkmcnt(0)
	v_add_f32_e32 v8, v8, v9
	v_mov_b32_e32 v244, v8
	v_mov_b32_e32 v9, v8
	s_nop 1
	v_permlane32_swap_b32_e32 v244, v9
	global_store_dwordx4 v[74:75], v[10:13], off offset:2304
	s_waitcnt lgkmcnt(0)
	v_add_f32_e32 v176, v8, v9
	v_mov_b32_e32 v178, v72
	v_mov_b32_e32 v179, v73
	s_waitcnt lgkmcnt(0)
	global_load_dwordx4 v[8:11], v[78:79], off offset:256
	s_and_saveexec_b64 s[10:11], s[4:5]
	global_atomic_add_f32 v[178:179], v176, off
	s_mov_b64 exec, s[10:11]
	v_pk_add_f32 v[6:7], v[6:7], v[70:71]
	v_pk_add_f32 v[4:5], v[4:5], v[68:69]
	v_pk_add_f32 v[0:1], v[0:1], v[64:65]
	v_mul_f32_e32 v5, 0xbfb8aa3b, v5
	v_mul_f32_e32 v7, 0xbfb8aa3b, v7
	v_pk_add_f32 v[2:3], v[2:3], v[66:67]
	v_mul_f32_e32 v4, 0xbfb8aa3b, v4
	v_mul_f32_e32 v6, 0xbfb8aa3b, v6
	v_mul_f32_e32 v0, 0xbfb8aa3b, v0
	v_mul_f32_e32 v1, 0xbfb8aa3b, v1
	v_exp_f32_e32 v5, v5
	v_exp_f32_e32 v7, v7
	v_mul_f32_e32 v2, 0xbfb8aa3b, v2
	v_mul_f32_e32 v3, 0xbfb8aa3b, v3
	v_exp_f32_e32 v4, v4
	v_exp_f32_e32 v6, v6
	v_exp_f32_e32 v0, v0
	v_exp_f32_e32 v1, v1
	v_exp_f32_e32 v2, v2
	v_exp_f32_e32 v3, v3
	v_add_f32_e32 v5, 1.0, v5
	v_add_f32_e32 v7, 1.0, v7
	v_add_f32_e32 v4, 1.0, v4
	v_add_f32_e32 v6, 1.0, v6
	v_add_f32_e32 v0, 1.0, v0
	v_add_f32_e32 v1, 1.0, v1
	v_rcp_f32_e32 v5, v5
	v_rcp_f32_e32 v7, v7
	v_add_f32_e32 v2, 1.0, v2
	v_add_f32_e32 v3, 1.0, v3
	v_rcp_f32_e32 v4, v4
	v_rcp_f32_e32 v6, v6
	v_rcp_f32_e32 v0, v0
	v_rcp_f32_e32 v1, v1
	v_rcp_f32_e32 v2, v2
	v_rcp_f32_e32 v3, v3
	s_waitcnt vmcnt(1)
	v_lshlrev_b32_e32 v12, 16, v8
	v_and_b32_e32 v8, 0xffff0000, v8
	v_lshlrev_b32_e32 v13, 16, v9
	v_and_b32_e32 v9, 0xffff0000, v9
	v_lshlrev_b32_e32 v14, 16, v10
	v_and_b32_e32 v10, 0xffff0000, v10
	v_mul_f32_e32 v5, v5, v8
	v_mul_f32_e32 v7, v7, v9
	v_lshlrev_b32_e32 v15, 16, v11
	v_and_b32_e32 v11, 0xffff0000, v11
	v_mul_f32_e32 v4, v4, v12
	v_mul_f32_e32 v6, v6, v13
	v_mul_f32_e32 v8, v0, v14
	v_mul_f32_e32 v9, v1, v10
	v_mul_f32_e32 v0, v5, v5
	v_mul_f32_e32 v1, v7, v7
	v_mul_f32_e32 v10, v2, v15
	v_mul_f32_e32 v11, v3, v11
	v_mul_f32_e32 v2, v9, v9
	v_fmac_f32_e32 v0, v4, v4
	v_fmac_f32_e32 v1, v6, v6
	v_mul_f32_e32 v3, v11, v11
	v_fmac_f32_e32 v2, v8, v8
	v_add_f32_e32 v0, v0, v1
	v_add_f32_e32 v0, v2, v0
	v_fmac_f32_e32 v3, v10, v10
	v_add_f32_e32 v0, v3, v0
	v_mov_b32_e32 v244, v0
	v_mov_b32_e32 v1, v0
	s_nop 1
	v_permlane16_swap_b32_e32 v244, v1
	v_cvt_pk_bf16_f32 v2, v4, v5
	v_cvt_pk_bf16_f32 v3, v6, v7
	v_cvt_pk_bf16_f32 v4, v8, v9
	v_cvt_pk_bf16_f32 v5, v10, v11
	s_waitcnt lgkmcnt(0)
	v_add_f32_e32 v0, v0, v1
	v_mov_b32_e32 v244, v0
	v_mov_b32_e32 v1, v0
	s_nop 1
	v_permlane32_swap_b32_e32 v244, v1
	global_store_dwordx4 v[86:87], v[2:5], off offset:2304
	s_and_saveexec_b64 s[10:11], s[4:5]
	s_cbranch_execz .LBB0_631
	s_waitcnt lgkmcnt(0)
	v_add_f32_e32 v0, v0, v1
	global_atomic_add_f32 v[76:77], v0, off
